# LRU loops rewritten + merge-phase gate epilogue rewritten (T and merged-tile loads hoisted 4 row groups deep)
# speedup vs baseline: 1.0330x; 1.0091x over previous
; #define LAS __attribute__((address_space(3)))
; __device__ __forceinline__ u32x4 pack8(f32x4 a, f32x4 b) { u32x4 w; w.x = cvt_pk_bf16(a[0], a[1]); w.y = cvt_pk_bf16(a[2], a[3]); w.z = cvt_pk_bf16(b[0], b[1]); w.w = cvt_pk_bf16(b[2], b[3]); return w; }
; __device__ __forceinline__ void unpack8(u32x4 w, f32x4& a, f32x4& b) { a = (f32x4){bflo(w.x), bfhi(w.x), bflo(w.y), bfhi(w.y)}; b = (f32x4){bflo(w.z), bfhi(w.z), bflo(w.w), bfhi(w.w)}; }
; __device__ __forceinline__ float sigmoidf_(float x) { return __builtin_amdgcn_rcpf(1.f + __builtin_amdgcn_exp2f(-1.4426950408889634f * x)); }
;     __device__ __forceinline__ void operator()(AccRef acc, const MUnit& u, int wr, int wc, int fr, int fq) const {
;     ...
;             const LAS float* rsl = (const LAS float*)(lds_rs + RSL_OFF) + (u.ui >> 3) * 256;
;             u32x4 tq[2][4][2];
; #pragma unroll
;             for (int ai = 0; ai < 2; ++ai)
; #pragma unroll
;                 for (int m = 0; m < 4; ++m)
; #pragma unroll
;                     for (int bj = 0; bj < 2; ++bj) tq[ai][m][bj] = *(const u32x4*)(tn + (size_t)(u.pm * 256 + ai * 128 + wr * 64 + m * 16 + fr) * 1024 + col0 + bj * 128);
;             EPI_ROWS_BEGIN
;                 const float r = rsl[row & 255]; const float ts = (n == 2) ? rsl[1024 + (row & 255)] : 1.f;
; #pragma unroll
;                 for (int bj = 0; bj < 2; ++bj) {
;                     const size_t off = (size_t)row * 1024 + col0 + bj * 128;
;                     f32x4 t0, t1; unpack8(tq[ai][m][bj], t0, t1); t0 = t0 * ts; t1 = t1 * ts;
;                     f32x4 g0 = acc[ai][bj][m][0] * r, g1 = acc[ai][bj][m][1] * r;
; #pragma unroll
;                     for (int e = 0; e < 4; ++e) { g0[e] = sigmoidf_(g0[e]) * t0[e]; g1[e] = sigmoidf_(g1[e]) * t1[e]; }
;                     if (n > 0) { f32x4 p0, p1; unpack8(*(const u32x4*)(mb + off), p0, p1); g0 += p0; g1 += p1; }
;                     *(u32x4*)(mb + off) = pack8(g0, g1);
.LBB0_1334:
	s_lshl_b32 s21, s68, 8
	v_lshl_or_b32 v206, s67, 8, v247
	v_add_u32_e32 v208, s21, v237
	s_cmp_lg_u32 s66, 0
	v_ashrrev_i32_e32 v207, 31, v206
	v_ashrrev_i32_e32 v209, 31, v208
	s_cbranch_scc0 .LBB0_1389
	v_mov_b64_e32 v[230:231], 0x200
	v_mov_b64_e32 v[222:223], 0x1ff
	s_cmp_eq_u32 s31, 2
	s_cselect_b64 s[38:39], -1, 0
	s_cmp_gt_i32 s31, 0
	s_cselect_b64 s[8:9], -1, 0
	s_cmp_lg_u32 s31, 0
	s_cbranch_scc1 .Lgate_mb
	s_lshl_b32 s6, s68, 19
	s_lshl_b32 s23, s67, 9
	s_add_u32 s6, s6, s23
	v_lshlrev_b32_e32 v0, 11, v237
	v_lshl_add_u32 v0, v247, 1, v0
	v_add_u32_e32 v194, s6, v0
	v_mov_b32_e32 v0, v194
	global_load_dwordx4 v[130:133], v0, s[0:1]
	global_load_dwordx4 v[134:137], v0, s[0:1] offset:256
	v_add_u32_e32 v0, 0x8000, v194
	global_load_dwordx4 v[146:149], v0, s[0:1]
	global_load_dwordx4 v[150:153], v0, s[0:1] offset:256
	v_add_u32_e32 v0, 0x10000, v194
	global_load_dwordx4 v[162:165], v0, s[0:1]
	global_load_dwordx4 v[166:169], v0, s[0:1] offset:256
	v_add_u32_e32 v0, 0x18000, v194
	global_load_dwordx4 v[178:181], v0, s[0:1]
	global_load_dwordx4 v[182:185], v0, s[0:1] offset:256
	s_lshl_b32 s6, s65, 7
	s_and_b32 s6, s6, 0xfffffc00
	s_add_i32 s23, s6, 0x21000
	v_lshl_add_u32 v195, v237, 2, s23
	ds_read_b32 v205, v195 offset:0
	ds_read_b32 v250, v195 offset:4096
	s_waitcnt lgkmcnt(0)
	v_cndmask_b32_e64 v250, 1.0, v250, s[38:39]
	v_mul_f32_e32 v126, v126, v205
	v_mul_f32_e32 v127, v127, v205
	v_mul_f32_e32 v128, v128, v205
	v_mul_f32_e32 v129, v129, v205
	v_mul_f32_e32 v122, v122, v205
	v_mul_f32_e32 v123, v123, v205
	v_mul_f32_e32 v124, v124, v205
	v_mul_f32_e32 v125, v125, v205
	v_mul_f32_e32 v118, v118, v205
	v_mul_f32_e32 v119, v119, v205
	v_mul_f32_e32 v120, v120, v205
	v_mul_f32_e32 v121, v121, v205
	v_mul_f32_e32 v114, v114, v205
	v_mul_f32_e32 v115, v115, v205
	v_mul_f32_e32 v116, v116, v205
	v_mul_f32_e32 v117, v117, v205
	v_mul_f32_e32 v126, 0xbfb8aa3b, v126
	v_mul_f32_e32 v127, 0xbfb8aa3b, v127
	v_mul_f32_e32 v128, 0xbfb8aa3b, v128
	v_mul_f32_e32 v129, 0xbfb8aa3b, v129
	v_mul_f32_e32 v122, 0xbfb8aa3b, v122
	v_mul_f32_e32 v123, 0xbfb8aa3b, v123
	v_mul_f32_e32 v124, 0xbfb8aa3b, v124
	v_mul_f32_e32 v125, 0xbfb8aa3b, v125
	v_mul_f32_e32 v118, 0xbfb8aa3b, v118
	v_mul_f32_e32 v119, 0xbfb8aa3b, v119
	v_mul_f32_e32 v120, 0xbfb8aa3b, v120
	v_mul_f32_e32 v121, 0xbfb8aa3b, v121
	v_mul_f32_e32 v114, 0xbfb8aa3b, v114
	v_mul_f32_e32 v115, 0xbfb8aa3b, v115
	v_mul_f32_e32 v116, 0xbfb8aa3b, v116
	v_mul_f32_e32 v117, 0xbfb8aa3b, v117
	v_exp_f32_e32 v126, v126
	v_exp_f32_e32 v127, v127
	v_exp_f32_e32 v128, v128
	v_exp_f32_e32 v129, v129
	v_exp_f32_e32 v122, v122
	v_exp_f32_e32 v123, v123
	v_exp_f32_e32 v124, v124
	v_exp_f32_e32 v125, v125
	v_exp_f32_e32 v118, v118
	v_exp_f32_e32 v119, v119
	v_exp_f32_e32 v120, v120
	v_exp_f32_e32 v121, v121
	v_exp_f32_e32 v114, v114
	v_exp_f32_e32 v115, v115
	v_exp_f32_e32 v116, v116
	v_exp_f32_e32 v117, v117
	v_add_f32_e32 v126, 1.0, v126
	v_add_f32_e32 v127, 1.0, v127
	v_add_f32_e32 v128, 1.0, v128
	v_add_f32_e32 v129, 1.0, v129
	v_add_f32_e32 v122, 1.0, v122
	v_add_f32_e32 v123, 1.0, v123
	v_add_f32_e32 v124, 1.0, v124
	v_add_f32_e32 v125, 1.0, v125
	v_add_f32_e32 v118, 1.0, v118
	v_add_f32_e32 v119, 1.0, v119
	v_add_f32_e32 v120, 1.0, v120
	v_add_f32_e32 v121, 1.0, v121
	v_add_f32_e32 v114, 1.0, v114
	v_add_f32_e32 v115, 1.0, v115
	v_add_f32_e32 v116, 1.0, v116
	v_add_f32_e32 v117, 1.0, v117
	v_rcp_f32_e32 v126, v126
	v_rcp_f32_e32 v127, v127
	v_rcp_f32_e32 v128, v128
	v_rcp_f32_e32 v129, v129
	v_rcp_f32_e32 v122, v122
	v_rcp_f32_e32 v123, v123
	v_rcp_f32_e32 v124, v124
	v_rcp_f32_e32 v125, v125
	v_rcp_f32_e32 v118, v118
	v_rcp_f32_e32 v119, v119
	v_rcp_f32_e32 v120, v120
	v_rcp_f32_e32 v121, v121
	v_rcp_f32_e32 v114, v114
	v_rcp_f32_e32 v115, v115
	v_rcp_f32_e32 v116, v116
	v_rcp_f32_e32 v117, v117
	s_waitcnt vmcnt(6)
	v_mov_b32_e32 v203, v194
	v_lshlrev_b32_e32 v210, 16, v130
	v_and_b32_e32 v211, 0xffff0000, v130
	v_lshlrev_b32_e32 v212, 16, v131
	v_and_b32_e32 v213, 0xffff0000, v131
	v_lshlrev_b32_e32 v214, 16, v132
	v_and_b32_e32 v215, 0xffff0000, v132
	v_lshlrev_b32_e32 v216, 16, v133
	v_and_b32_e32 v217, 0xffff0000, v133
	v_pk_mul_f32 v[210:211], v[250:251], v[210:211] op_sel_hi:[0,1]
	v_pk_mul_f32 v[212:213], v[250:251], v[212:213] op_sel_hi:[0,1]
	v_pk_mul_f32 v[214:215], v[250:251], v[214:215] op_sel_hi:[0,1]
	v_pk_mul_f32 v[216:217], v[250:251], v[216:217] op_sel_hi:[0,1]
	v_pk_mul_f32 v[210:211], v[126:127], v[210:211]
	v_pk_mul_f32 v[212:213], v[128:129], v[212:213]
	v_pk_mul_f32 v[214:215], v[122:123], v[214:215]
	v_pk_mul_f32 v[216:217], v[124:125], v[216:217]
	v_cvt_pk_bf16_f32 v130, v210, v211
	v_cvt_pk_bf16_f32 v131, v212, v213
	v_cvt_pk_bf16_f32 v132, v214, v215
	v_cvt_pk_bf16_f32 v133, v216, v217
	global_store_dwordx4 v203, v[130:133], s[16:17]
	v_lshlrev_b32_e32 v210, 16, v134
	v_and_b32_e32 v211, 0xffff0000, v134
	v_lshlrev_b32_e32 v212, 16, v135
	v_and_b32_e32 v213, 0xffff0000, v135
	v_lshlrev_b32_e32 v214, 16, v136
	v_and_b32_e32 v215, 0xffff0000, v136
	v_lshlrev_b32_e32 v216, 16, v137
	v_and_b32_e32 v217, 0xffff0000, v137
	v_pk_mul_f32 v[210:211], v[250:251], v[210:211] op_sel_hi:[0,1]
	v_pk_mul_f32 v[212:213], v[250:251], v[212:213] op_sel_hi:[0,1]
	v_pk_mul_f32 v[214:215], v[250:251], v[214:215] op_sel_hi:[0,1]
	v_pk_mul_f32 v[216:217], v[250:251], v[216:217] op_sel_hi:[0,1]
	v_pk_mul_f32 v[210:211], v[118:119], v[210:211]
	v_pk_mul_f32 v[212:213], v[120:121], v[212:213]
	v_pk_mul_f32 v[214:215], v[114:115], v[214:215]
	v_pk_mul_f32 v[216:217], v[116:117], v[216:217]
	v_cvt_pk_bf16_f32 v134, v210, v211
	v_cvt_pk_bf16_f32 v135, v212, v213
	v_cvt_pk_bf16_f32 v136, v214, v215
	v_cvt_pk_bf16_f32 v137, v216, v217
	global_store_dwordx4 v203, v[134:137], s[16:17] offset:256
	s_nop 1
	v_add_u32_e32 v0, 0x40000, v194
	global_load_dwordx4 v[130:133], v0, s[0:1]
	global_load_dwordx4 v[134:137], v0, s[0:1] offset:256
	ds_read_b32 v205, v195 offset:64
	ds_read_b32 v250, v195 offset:4160
	s_waitcnt lgkmcnt(0)
; __device__ __forceinline__ u32x4 pack8(f32x4 a, f32x4 b) { u32x4 w; w.x = cvt_pk_bf16(a[0], a[1]); w.y = cvt_pk_bf16(a[2], a[3]); w.z = cvt_pk_bf16(b[0], b[1]); w.w = cvt_pk_bf16(b[2], b[3]); return w; }
; __device__ __forceinline__ void unpack8(u32x4 w, f32x4& a, f32x4& b) { a = (f32x4){bflo(w.x), bfhi(w.x), bflo(w.y), bfhi(w.y)}; b = (f32x4){bflo(w.z), bfhi(w.z), bflo(w.w), bfhi(w.w)}; }
; __device__ __forceinline__ float sigmoidf_(float x) { return __builtin_amdgcn_rcpf(1.f + __builtin_amdgcn_exp2f(-1.4426950408889634f * x)); }
;     __device__ __forceinline__ void operator()(AccRef acc, const MUnit& u, int wr, int wc, int fr, int fq) const {
;     ...
;             EPI_ROWS_BEGIN
;                 const float r = rsl[row & 255]; const float ts = (n == 2) ? rsl[1024 + (row & 255)] : 1.f;
; #pragma unroll
;                 for (int bj = 0; bj < 2; ++bj) {
;                     const size_t off = (size_t)row * 1024 + col0 + bj * 128;
;                     f32x4 t0, t1; unpack8(tq[ai][m][bj], t0, t1); t0 = t0 * ts; t1 = t1 * ts;
;                     f32x4 g0 = acc[ai][bj][m][0] * r, g1 = acc[ai][bj][m][1] * r;
; #pragma unroll
;                     for (int e = 0; e < 4; ++e) { g0[e] = sigmoidf_(g0[e]) * t0[e]; g1[e] = sigmoidf_(g1[e]) * t1[e]; }
;                     if (n > 0) { f32x4 p0, p1; unpack8(*(const u32x4*)(mb + off), p0, p1); g0 += p0; g1 += p1; }
;                     *(u32x4*)(mb + off) = pack8(g0, g1);
	v_cndmask_b32_e64 v250, 1.0, v250, s[38:39]
	v_mul_f32_e32 v110, v110, v205
	v_mul_f32_e32 v111, v111, v205
	v_mul_f32_e32 v112, v112, v205
	v_mul_f32_e32 v113, v113, v205
	v_mul_f32_e32 v106, v106, v205
	v_mul_f32_e32 v107, v107, v205
	v_mul_f32_e32 v108, v108, v205
	v_mul_f32_e32 v109, v109, v205
	v_mul_f32_e32 v102, v102, v205
	v_mul_f32_e32 v103, v103, v205
	v_mul_f32_e32 v104, v104, v205
	v_mul_f32_e32 v105, v105, v205
	v_mul_f32_e32 v98, v98, v205
	v_mul_f32_e32 v99, v99, v205
	v_mul_f32_e32 v100, v100, v205
	v_mul_f32_e32 v101, v101, v205
	v_mul_f32_e32 v110, 0xbfb8aa3b, v110
	v_mul_f32_e32 v111, 0xbfb8aa3b, v111
	v_mul_f32_e32 v112, 0xbfb8aa3b, v112
	v_mul_f32_e32 v113, 0xbfb8aa3b, v113
	v_mul_f32_e32 v106, 0xbfb8aa3b, v106
	v_mul_f32_e32 v107, 0xbfb8aa3b, v107
	v_mul_f32_e32 v108, 0xbfb8aa3b, v108
	v_mul_f32_e32 v109, 0xbfb8aa3b, v109
	v_mul_f32_e32 v102, 0xbfb8aa3b, v102
	v_mul_f32_e32 v103, 0xbfb8aa3b, v103
	v_mul_f32_e32 v104, 0xbfb8aa3b, v104
	v_mul_f32_e32 v105, 0xbfb8aa3b, v105
	v_mul_f32_e32 v98, 0xbfb8aa3b, v98
	v_mul_f32_e32 v99, 0xbfb8aa3b, v99
	v_mul_f32_e32 v100, 0xbfb8aa3b, v100
	v_mul_f32_e32 v101, 0xbfb8aa3b, v101
	v_exp_f32_e32 v110, v110
	v_exp_f32_e32 v111, v111
	v_exp_f32_e32 v112, v112
	v_exp_f32_e32 v113, v113
	v_exp_f32_e32 v106, v106
	v_exp_f32_e32 v107, v107
	v_exp_f32_e32 v108, v108
	v_exp_f32_e32 v109, v109
	v_exp_f32_e32 v102, v102
	v_exp_f32_e32 v103, v103
	v_exp_f32_e32 v104, v104
	v_exp_f32_e32 v105, v105
	v_exp_f32_e32 v98, v98
	v_exp_f32_e32 v99, v99
	v_exp_f32_e32 v100, v100
	v_exp_f32_e32 v101, v101
	v_add_f32_e32 v110, 1.0, v110
	v_add_f32_e32 v111, 1.0, v111
	v_add_f32_e32 v112, 1.0, v112
	v_add_f32_e32 v113, 1.0, v113
	v_add_f32_e32 v106, 1.0, v106
	v_add_f32_e32 v107, 1.0, v107
	v_add_f32_e32 v108, 1.0, v108
	v_add_f32_e32 v109, 1.0, v109
	v_add_f32_e32 v102, 1.0, v102
	v_add_f32_e32 v103, 1.0, v103
	v_add_f32_e32 v104, 1.0, v104
	v_add_f32_e32 v105, 1.0, v105
	v_add_f32_e32 v98, 1.0, v98
	v_add_f32_e32 v99, 1.0, v99
	v_add_f32_e32 v100, 1.0, v100
	v_add_f32_e32 v101, 1.0, v101
	v_rcp_f32_e32 v110, v110
	v_rcp_f32_e32 v111, v111
	v_rcp_f32_e32 v112, v112
	v_rcp_f32_e32 v113, v113
	v_rcp_f32_e32 v106, v106
	v_rcp_f32_e32 v107, v107
	v_rcp_f32_e32 v108, v108
	v_rcp_f32_e32 v109, v109
	v_rcp_f32_e32 v102, v102
	v_rcp_f32_e32 v103, v103
	v_rcp_f32_e32 v104, v104
	v_rcp_f32_e32 v105, v105
	v_rcp_f32_e32 v98, v98
	v_rcp_f32_e32 v99, v99
	v_rcp_f32_e32 v100, v100
	v_rcp_f32_e32 v101, v101
	s_waitcnt vmcnt(8)
	v_add_u32_e32 v203, 0x8000, v194
	v_lshlrev_b32_e32 v210, 16, v146
	v_and_b32_e32 v211, 0xffff0000, v146
	v_lshlrev_b32_e32 v212, 16, v147
	v_and_b32_e32 v213, 0xffff0000, v147
	v_lshlrev_b32_e32 v214, 16, v148
	v_and_b32_e32 v215, 0xffff0000, v148
	v_lshlrev_b32_e32 v216, 16, v149
	v_and_b32_e32 v217, 0xffff0000, v149
	v_pk_mul_f32 v[210:211], v[250:251], v[210:211] op_sel_hi:[0,1]
	v_pk_mul_f32 v[212:213], v[250:251], v[212:213] op_sel_hi:[0,1]
	v_pk_mul_f32 v[214:215], v[250:251], v[214:215] op_sel_hi:[0,1]
	v_pk_mul_f32 v[216:217], v[250:251], v[216:217] op_sel_hi:[0,1]
	v_pk_mul_f32 v[210:211], v[110:111], v[210:211]
	v_pk_mul_f32 v[212:213], v[112:113], v[212:213]
	v_pk_mul_f32 v[214:215], v[106:107], v[214:215]
	v_pk_mul_f32 v[216:217], v[108:109], v[216:217]
	v_cvt_pk_bf16_f32 v146, v210, v211
	v_cvt_pk_bf16_f32 v147, v212, v213
	v_cvt_pk_bf16_f32 v148, v214, v215
	v_cvt_pk_bf16_f32 v149, v216, v217
	global_store_dwordx4 v203, v[146:149], s[16:17]
	v_lshlrev_b32_e32 v210, 16, v150
	v_and_b32_e32 v211, 0xffff0000, v150
	v_lshlrev_b32_e32 v212, 16, v151
	v_and_b32_e32 v213, 0xffff0000, v151
	v_lshlrev_b32_e32 v214, 16, v152
	v_and_b32_e32 v215, 0xffff0000, v152
	v_lshlrev_b32_e32 v216, 16, v153
	v_and_b32_e32 v217, 0xffff0000, v153
	v_pk_mul_f32 v[210:211], v[250:251], v[210:211] op_sel_hi:[0,1]
	v_pk_mul_f32 v[212:213], v[250:251], v[212:213] op_sel_hi:[0,1]
	v_pk_mul_f32 v[214:215], v[250:251], v[214:215] op_sel_hi:[0,1]
	v_pk_mul_f32 v[216:217], v[250:251], v[216:217] op_sel_hi:[0,1]
	v_pk_mul_f32 v[210:211], v[102:103], v[210:211]
	v_pk_mul_f32 v[212:213], v[104:105], v[212:213]
	v_pk_mul_f32 v[214:215], v[98:99], v[214:215]
	v_pk_mul_f32 v[216:217], v[100:101], v[216:217]
	v_cvt_pk_bf16_f32 v150, v210, v211
	v_cvt_pk_bf16_f32 v151, v212, v213
	v_cvt_pk_bf16_f32 v152, v214, v215
	v_cvt_pk_bf16_f32 v153, v216, v217
	global_store_dwordx4 v203, v[150:153], s[16:17] offset:256
	s_nop 1
	v_add_u32_e32 v0, 0x48000, v194
	global_load_dwordx4 v[146:149], v0, s[0:1]
	global_load_dwordx4 v[150:153], v0, s[0:1] offset:256
	ds_read_b32 v205, v195 offset:128
	ds_read_b32 v250, v195 offset:4224
	s_waitcnt lgkmcnt(0)
; __device__ __forceinline__ u32x4 pack8(f32x4 a, f32x4 b) { u32x4 w; w.x = cvt_pk_bf16(a[0], a[1]); w.y = cvt_pk_bf16(a[2], a[3]); w.z = cvt_pk_bf16(b[0], b[1]); w.w = cvt_pk_bf16(b[2], b[3]); return w; }
; __device__ __forceinline__ void unpack8(u32x4 w, f32x4& a, f32x4& b) { a = (f32x4){bflo(w.x), bfhi(w.x), bflo(w.y), bfhi(w.y)}; b = (f32x4){bflo(w.z), bfhi(w.z), bflo(w.w), bfhi(w.w)}; }
; __device__ __forceinline__ float sigmoidf_(float x) { return __builtin_amdgcn_rcpf(1.f + __builtin_amdgcn_exp2f(-1.4426950408889634f * x)); }
;     __device__ __forceinline__ void operator()(AccRef acc, const MUnit& u, int wr, int wc, int fr, int fq) const {
;     ...
;             EPI_ROWS_BEGIN
;                 const float r = rsl[row & 255]; const float ts = (n == 2) ? rsl[1024 + (row & 255)] : 1.f;
; #pragma unroll
;                 for (int bj = 0; bj < 2; ++bj) {
;                     const size_t off = (size_t)row * 1024 + col0 + bj * 128;
;                     f32x4 t0, t1; unpack8(tq[ai][m][bj], t0, t1); t0 = t0 * ts; t1 = t1 * ts;
;                     f32x4 g0 = acc[ai][bj][m][0] * r, g1 = acc[ai][bj][m][1] * r;
; #pragma unroll
;                     for (int e = 0; e < 4; ++e) { g0[e] = sigmoidf_(g0[e]) * t0[e]; g1[e] = sigmoidf_(g1[e]) * t1[e]; }
;                     if (n > 0) { f32x4 p0, p1; unpack8(*(const u32x4*)(mb + off), p0, p1); g0 += p0; g1 += p1; }
;                     *(u32x4*)(mb + off) = pack8(g0, g1);
	v_cndmask_b32_e64 v250, 1.0, v250, s[38:39]
	v_mul_f32_e32 v94, v94, v205
	v_mul_f32_e32 v95, v95, v205
	v_mul_f32_e32 v96, v96, v205
	v_mul_f32_e32 v97, v97, v205
	v_mul_f32_e32 v90, v90, v205
	v_mul_f32_e32 v91, v91, v205
	v_mul_f32_e32 v92, v92, v205
	v_mul_f32_e32 v93, v93, v205
	v_mul_f32_e32 v86, v86, v205
	v_mul_f32_e32 v87, v87, v205
	v_mul_f32_e32 v88, v88, v205
	v_mul_f32_e32 v89, v89, v205
	v_mul_f32_e32 v82, v82, v205
	v_mul_f32_e32 v83, v83, v205
	v_mul_f32_e32 v84, v84, v205
	v_mul_f32_e32 v85, v85, v205
	v_mul_f32_e32 v94, 0xbfb8aa3b, v94
	v_mul_f32_e32 v95, 0xbfb8aa3b, v95
	v_mul_f32_e32 v96, 0xbfb8aa3b, v96
	v_mul_f32_e32 v97, 0xbfb8aa3b, v97
	v_mul_f32_e32 v90, 0xbfb8aa3b, v90
	v_mul_f32_e32 v91, 0xbfb8aa3b, v91
	v_mul_f32_e32 v92, 0xbfb8aa3b, v92
	v_mul_f32_e32 v93, 0xbfb8aa3b, v93
	v_mul_f32_e32 v86, 0xbfb8aa3b, v86
	v_mul_f32_e32 v87, 0xbfb8aa3b, v87
	v_mul_f32_e32 v88, 0xbfb8aa3b, v88
	v_mul_f32_e32 v89, 0xbfb8aa3b, v89
	v_mul_f32_e32 v82, 0xbfb8aa3b, v82
	v_mul_f32_e32 v83, 0xbfb8aa3b, v83
	v_mul_f32_e32 v84, 0xbfb8aa3b, v84
	v_mul_f32_e32 v85, 0xbfb8aa3b, v85
	v_exp_f32_e32 v94, v94
	v_exp_f32_e32 v95, v95
	v_exp_f32_e32 v96, v96
	v_exp_f32_e32 v97, v97
	v_exp_f32_e32 v90, v90
	v_exp_f32_e32 v91, v91
	v_exp_f32_e32 v92, v92
	v_exp_f32_e32 v93, v93
	v_exp_f32_e32 v86, v86
	v_exp_f32_e32 v87, v87
	v_exp_f32_e32 v88, v88
	v_exp_f32_e32 v89, v89
	v_exp_f32_e32 v82, v82
	v_exp_f32_e32 v83, v83
	v_exp_f32_e32 v84, v84
	v_exp_f32_e32 v85, v85
	v_add_f32_e32 v94, 1.0, v94
	v_add_f32_e32 v95, 1.0, v95
	v_add_f32_e32 v96, 1.0, v96
	v_add_f32_e32 v97, 1.0, v97
	v_add_f32_e32 v90, 1.0, v90
	v_add_f32_e32 v91, 1.0, v91
	v_add_f32_e32 v92, 1.0, v92
	v_add_f32_e32 v93, 1.0, v93
	v_add_f32_e32 v86, 1.0, v86
	v_add_f32_e32 v87, 1.0, v87
	v_add_f32_e32 v88, 1.0, v88
	v_add_f32_e32 v89, 1.0, v89
	v_add_f32_e32 v82, 1.0, v82
	v_add_f32_e32 v83, 1.0, v83
	v_add_f32_e32 v84, 1.0, v84
	v_add_f32_e32 v85, 1.0, v85
	v_rcp_f32_e32 v94, v94
	v_rcp_f32_e32 v95, v95
	v_rcp_f32_e32 v96, v96
	v_rcp_f32_e32 v97, v97
	v_rcp_f32_e32 v90, v90
	v_rcp_f32_e32 v91, v91
	v_rcp_f32_e32 v92, v92
	v_rcp_f32_e32 v93, v93
	v_rcp_f32_e32 v86, v86
	v_rcp_f32_e32 v87, v87
	v_rcp_f32_e32 v88, v88
	v_rcp_f32_e32 v89, v89
	v_rcp_f32_e32 v82, v82
	v_rcp_f32_e32 v83, v83
	v_rcp_f32_e32 v84, v84
	v_rcp_f32_e32 v85, v85
	s_waitcnt vmcnt(10)
	v_add_u32_e32 v203, 0x10000, v194
	v_lshlrev_b32_e32 v210, 16, v162
	v_and_b32_e32 v211, 0xffff0000, v162
	v_lshlrev_b32_e32 v212, 16, v163
	v_and_b32_e32 v213, 0xffff0000, v163
	v_lshlrev_b32_e32 v214, 16, v164
	v_and_b32_e32 v215, 0xffff0000, v164
	v_lshlrev_b32_e32 v216, 16, v165
	v_and_b32_e32 v217, 0xffff0000, v165
	v_pk_mul_f32 v[210:211], v[250:251], v[210:211] op_sel_hi:[0,1]
	v_pk_mul_f32 v[212:213], v[250:251], v[212:213] op_sel_hi:[0,1]
	v_pk_mul_f32 v[214:215], v[250:251], v[214:215] op_sel_hi:[0,1]
	v_pk_mul_f32 v[216:217], v[250:251], v[216:217] op_sel_hi:[0,1]
	v_pk_mul_f32 v[210:211], v[94:95], v[210:211]
	v_pk_mul_f32 v[212:213], v[96:97], v[212:213]
	v_pk_mul_f32 v[214:215], v[90:91], v[214:215]
	v_pk_mul_f32 v[216:217], v[92:93], v[216:217]
	v_cvt_pk_bf16_f32 v162, v210, v211
	v_cvt_pk_bf16_f32 v163, v212, v213
	v_cvt_pk_bf16_f32 v164, v214, v215
	v_cvt_pk_bf16_f32 v165, v216, v217
	global_store_dwordx4 v203, v[162:165], s[16:17]
	v_lshlrev_b32_e32 v210, 16, v166
	v_and_b32_e32 v211, 0xffff0000, v166
	v_lshlrev_b32_e32 v212, 16, v167
	v_and_b32_e32 v213, 0xffff0000, v167
	v_lshlrev_b32_e32 v214, 16, v168
	v_and_b32_e32 v215, 0xffff0000, v168
	v_lshlrev_b32_e32 v216, 16, v169
	v_and_b32_e32 v217, 0xffff0000, v169
	v_pk_mul_f32 v[210:211], v[250:251], v[210:211] op_sel_hi:[0,1]
	v_pk_mul_f32 v[212:213], v[250:251], v[212:213] op_sel_hi:[0,1]
	v_pk_mul_f32 v[214:215], v[250:251], v[214:215] op_sel_hi:[0,1]
	v_pk_mul_f32 v[216:217], v[250:251], v[216:217] op_sel_hi:[0,1]
	v_pk_mul_f32 v[210:211], v[86:87], v[210:211]
	v_pk_mul_f32 v[212:213], v[88:89], v[212:213]
	v_pk_mul_f32 v[214:215], v[82:83], v[214:215]
	v_pk_mul_f32 v[216:217], v[84:85], v[216:217]
	v_cvt_pk_bf16_f32 v166, v210, v211
	v_cvt_pk_bf16_f32 v167, v212, v213
	v_cvt_pk_bf16_f32 v168, v214, v215
	v_cvt_pk_bf16_f32 v169, v216, v217
	global_store_dwordx4 v203, v[166:169], s[16:17] offset:256
	s_nop 1
	v_add_u32_e32 v0, 0x50000, v194
	global_load_dwordx4 v[162:165], v0, s[0:1]
	global_load_dwordx4 v[166:169], v0, s[0:1] offset:256
	ds_read_b32 v205, v195 offset:192
	ds_read_b32 v250, v195 offset:4288
	s_waitcnt lgkmcnt(0)
; __device__ __forceinline__ u32x4 pack8(f32x4 a, f32x4 b) { u32x4 w; w.x = cvt_pk_bf16(a[0], a[1]); w.y = cvt_pk_bf16(a[2], a[3]); w.z = cvt_pk_bf16(b[0], b[1]); w.w = cvt_pk_bf16(b[2], b[3]); return w; }
; __device__ __forceinline__ void unpack8(u32x4 w, f32x4& a, f32x4& b) { a = (f32x4){bflo(w.x), bfhi(w.x), bflo(w.y), bfhi(w.y)}; b = (f32x4){bflo(w.z), bfhi(w.z), bflo(w.w), bfhi(w.w)}; }
; __device__ __forceinline__ float sigmoidf_(float x) { return __builtin_amdgcn_rcpf(1.f + __builtin_amdgcn_exp2f(-1.4426950408889634f * x)); }
;     __device__ __forceinline__ void operator()(AccRef acc, const MUnit& u, int wr, int wc, int fr, int fq) const {
;     ...
;             EPI_ROWS_BEGIN
;                 const float r = rsl[row & 255]; const float ts = (n == 2) ? rsl[1024 + (row & 255)] : 1.f;
; #pragma unroll
;                 for (int bj = 0; bj < 2; ++bj) {
;                     const size_t off = (size_t)row * 1024 + col0 + bj * 128;
;                     f32x4 t0, t1; unpack8(tq[ai][m][bj], t0, t1); t0 = t0 * ts; t1 = t1 * ts;
;                     f32x4 g0 = acc[ai][bj][m][0] * r, g1 = acc[ai][bj][m][1] * r;
; #pragma unroll
;                     for (int e = 0; e < 4; ++e) { g0[e] = sigmoidf_(g0[e]) * t0[e]; g1[e] = sigmoidf_(g1[e]) * t1[e]; }
;                     if (n > 0) { f32x4 p0, p1; unpack8(*(const u32x4*)(mb + off), p0, p1); g0 += p0; g1 += p1; }
;                     *(u32x4*)(mb + off) = pack8(g0, g1);
	v_cndmask_b32_e64 v250, 1.0, v250, s[38:39]
	v_mul_f32_e32 v78, v78, v205
	v_mul_f32_e32 v79, v79, v205
	v_mul_f32_e32 v80, v80, v205
	v_mul_f32_e32 v81, v81, v205
	v_mul_f32_e32 v74, v74, v205
	v_mul_f32_e32 v75, v75, v205
	v_mul_f32_e32 v76, v76, v205
	v_mul_f32_e32 v77, v77, v205
	v_mul_f32_e32 v70, v70, v205
	v_mul_f32_e32 v71, v71, v205
	v_mul_f32_e32 v72, v72, v205
	v_mul_f32_e32 v73, v73, v205
	v_mul_f32_e32 v66, v66, v205
	v_mul_f32_e32 v67, v67, v205
	v_mul_f32_e32 v68, v68, v205
	v_mul_f32_e32 v69, v69, v205
	v_mul_f32_e32 v78, 0xbfb8aa3b, v78
	v_mul_f32_e32 v79, 0xbfb8aa3b, v79
	v_mul_f32_e32 v80, 0xbfb8aa3b, v80
	v_mul_f32_e32 v81, 0xbfb8aa3b, v81
	v_mul_f32_e32 v74, 0xbfb8aa3b, v74
	v_mul_f32_e32 v75, 0xbfb8aa3b, v75
	v_mul_f32_e32 v76, 0xbfb8aa3b, v76
	v_mul_f32_e32 v77, 0xbfb8aa3b, v77
	v_mul_f32_e32 v70, 0xbfb8aa3b, v70
	v_mul_f32_e32 v71, 0xbfb8aa3b, v71
	v_mul_f32_e32 v72, 0xbfb8aa3b, v72
	v_mul_f32_e32 v73, 0xbfb8aa3b, v73
	v_mul_f32_e32 v66, 0xbfb8aa3b, v66
	v_mul_f32_e32 v67, 0xbfb8aa3b, v67
	v_mul_f32_e32 v68, 0xbfb8aa3b, v68
	v_mul_f32_e32 v69, 0xbfb8aa3b, v69
	v_exp_f32_e32 v78, v78
	v_exp_f32_e32 v79, v79
	v_exp_f32_e32 v80, v80
	v_exp_f32_e32 v81, v81
	v_exp_f32_e32 v74, v74
	v_exp_f32_e32 v75, v75
	v_exp_f32_e32 v76, v76
	v_exp_f32_e32 v77, v77
	v_exp_f32_e32 v70, v70
	v_exp_f32_e32 v71, v71
	v_exp_f32_e32 v72, v72
	v_exp_f32_e32 v73, v73
	v_exp_f32_e32 v66, v66
	v_exp_f32_e32 v67, v67
	v_exp_f32_e32 v68, v68
	v_exp_f32_e32 v69, v69
	v_add_f32_e32 v78, 1.0, v78
	v_add_f32_e32 v79, 1.0, v79
	v_add_f32_e32 v80, 1.0, v80
	v_add_f32_e32 v81, 1.0, v81
	v_add_f32_e32 v74, 1.0, v74
	v_add_f32_e32 v75, 1.0, v75
	v_add_f32_e32 v76, 1.0, v76
	v_add_f32_e32 v77, 1.0, v77
	v_add_f32_e32 v70, 1.0, v70
	v_add_f32_e32 v71, 1.0, v71
	v_add_f32_e32 v72, 1.0, v72
	v_add_f32_e32 v73, 1.0, v73
	v_add_f32_e32 v66, 1.0, v66
	v_add_f32_e32 v67, 1.0, v67
	v_add_f32_e32 v68, 1.0, v68
	v_add_f32_e32 v69, 1.0, v69
	v_rcp_f32_e32 v78, v78
	v_rcp_f32_e32 v79, v79
	v_rcp_f32_e32 v80, v80
	v_rcp_f32_e32 v81, v81
	v_rcp_f32_e32 v74, v74
	v_rcp_f32_e32 v75, v75
	v_rcp_f32_e32 v76, v76
	v_rcp_f32_e32 v77, v77
	v_rcp_f32_e32 v70, v70
	v_rcp_f32_e32 v71, v71
	v_rcp_f32_e32 v72, v72
	v_rcp_f32_e32 v73, v73
	v_rcp_f32_e32 v66, v66
	v_rcp_f32_e32 v67, v67
	v_rcp_f32_e32 v68, v68
	v_rcp_f32_e32 v69, v69
	s_waitcnt vmcnt(12)
	v_add_u32_e32 v203, 0x18000, v194
	v_lshlrev_b32_e32 v210, 16, v178
	v_and_b32_e32 v211, 0xffff0000, v178
	v_lshlrev_b32_e32 v212, 16, v179
	v_and_b32_e32 v213, 0xffff0000, v179
	v_lshlrev_b32_e32 v214, 16, v180
	v_and_b32_e32 v215, 0xffff0000, v180
	v_lshlrev_b32_e32 v216, 16, v181
	v_and_b32_e32 v217, 0xffff0000, v181
	v_pk_mul_f32 v[210:211], v[250:251], v[210:211] op_sel_hi:[0,1]
	v_pk_mul_f32 v[212:213], v[250:251], v[212:213] op_sel_hi:[0,1]
	v_pk_mul_f32 v[214:215], v[250:251], v[214:215] op_sel_hi:[0,1]
	v_pk_mul_f32 v[216:217], v[250:251], v[216:217] op_sel_hi:[0,1]
	v_pk_mul_f32 v[210:211], v[78:79], v[210:211]
	v_pk_mul_f32 v[212:213], v[80:81], v[212:213]
	v_pk_mul_f32 v[214:215], v[74:75], v[214:215]
	v_pk_mul_f32 v[216:217], v[76:77], v[216:217]
	v_cvt_pk_bf16_f32 v178, v210, v211
	v_cvt_pk_bf16_f32 v179, v212, v213
	v_cvt_pk_bf16_f32 v180, v214, v215
	v_cvt_pk_bf16_f32 v181, v216, v217
	global_store_dwordx4 v203, v[178:181], s[16:17]
	v_lshlrev_b32_e32 v210, 16, v182
	v_and_b32_e32 v211, 0xffff0000, v182
	v_lshlrev_b32_e32 v212, 16, v183
	v_and_b32_e32 v213, 0xffff0000, v183
	v_lshlrev_b32_e32 v214, 16, v184
	v_and_b32_e32 v215, 0xffff0000, v184
	v_lshlrev_b32_e32 v216, 16, v185
	v_and_b32_e32 v217, 0xffff0000, v185
	v_pk_mul_f32 v[210:211], v[250:251], v[210:211] op_sel_hi:[0,1]
	v_pk_mul_f32 v[212:213], v[250:251], v[212:213] op_sel_hi:[0,1]
	v_pk_mul_f32 v[214:215], v[250:251], v[214:215] op_sel_hi:[0,1]
	v_pk_mul_f32 v[216:217], v[250:251], v[216:217] op_sel_hi:[0,1]
	v_pk_mul_f32 v[210:211], v[70:71], v[210:211]
	v_pk_mul_f32 v[212:213], v[72:73], v[212:213]
	v_pk_mul_f32 v[214:215], v[66:67], v[214:215]
	v_pk_mul_f32 v[216:217], v[68:69], v[216:217]
	v_cvt_pk_bf16_f32 v182, v210, v211
	v_cvt_pk_bf16_f32 v183, v212, v213
	v_cvt_pk_bf16_f32 v184, v214, v215
	v_cvt_pk_bf16_f32 v185, v216, v217
	global_store_dwordx4 v203, v[182:185], s[16:17] offset:256
	s_nop 1
	v_add_u32_e32 v0, 0x58000, v194
	global_load_dwordx4 v[178:181], v0, s[0:1]
	global_load_dwordx4 v[182:185], v0, s[0:1] offset:256
	ds_read_b32 v205, v195 offset:512
	ds_read_b32 v250, v195 offset:4608
	s_waitcnt lgkmcnt(0)
; __device__ __forceinline__ u32x4 pack8(f32x4 a, f32x4 b) { u32x4 w; w.x = cvt_pk_bf16(a[0], a[1]); w.y = cvt_pk_bf16(a[2], a[3]); w.z = cvt_pk_bf16(b[0], b[1]); w.w = cvt_pk_bf16(b[2], b[3]); return w; }
; __device__ __forceinline__ void unpack8(u32x4 w, f32x4& a, f32x4& b) { a = (f32x4){bflo(w.x), bfhi(w.x), bflo(w.y), bfhi(w.y)}; b = (f32x4){bflo(w.z), bfhi(w.z), bflo(w.w), bfhi(w.w)}; }
; __device__ __forceinline__ float sigmoidf_(float x) { return __builtin_amdgcn_rcpf(1.f + __builtin_amdgcn_exp2f(-1.4426950408889634f * x)); }
;     __device__ __forceinline__ void operator()(AccRef acc, const MUnit& u, int wr, int wc, int fr, int fq) const {
;     ...
;             EPI_ROWS_BEGIN
;                 const float r = rsl[row & 255]; const float ts = (n == 2) ? rsl[1024 + (row & 255)] : 1.f;
; #pragma unroll
;                 for (int bj = 0; bj < 2; ++bj) {
;                     const size_t off = (size_t)row * 1024 + col0 + bj * 128;
;                     f32x4 t0, t1; unpack8(tq[ai][m][bj], t0, t1); t0 = t0 * ts; t1 = t1 * ts;
;                     f32x4 g0 = acc[ai][bj][m][0] * r, g1 = acc[ai][bj][m][1] * r;
; #pragma unroll
;                     for (int e = 0; e < 4; ++e) { g0[e] = sigmoidf_(g0[e]) * t0[e]; g1[e] = sigmoidf_(g1[e]) * t1[e]; }
;                     if (n > 0) { f32x4 p0, p1; unpack8(*(const u32x4*)(mb + off), p0, p1); g0 += p0; g1 += p1; }
;                     *(u32x4*)(mb + off) = pack8(g0, g1);
	v_cndmask_b32_e64 v250, 1.0, v250, s[38:39]
	v_mul_f32_e32 v62, v62, v205
	v_mul_f32_e32 v63, v63, v205
	v_mul_f32_e32 v64, v64, v205
	v_mul_f32_e32 v65, v65, v205
	v_mul_f32_e32 v58, v58, v205
	v_mul_f32_e32 v59, v59, v205
	v_mul_f32_e32 v60, v60, v205
	v_mul_f32_e32 v61, v61, v205
	v_mul_f32_e32 v54, v54, v205
	v_mul_f32_e32 v55, v55, v205
	v_mul_f32_e32 v56, v56, v205
	v_mul_f32_e32 v57, v57, v205
	v_mul_f32_e32 v50, v50, v205
	v_mul_f32_e32 v51, v51, v205
	v_mul_f32_e32 v52, v52, v205
	v_mul_f32_e32 v53, v53, v205
	v_mul_f32_e32 v62, 0xbfb8aa3b, v62
	v_mul_f32_e32 v63, 0xbfb8aa3b, v63
	v_mul_f32_e32 v64, 0xbfb8aa3b, v64
	v_mul_f32_e32 v65, 0xbfb8aa3b, v65
	v_mul_f32_e32 v58, 0xbfb8aa3b, v58
	v_mul_f32_e32 v59, 0xbfb8aa3b, v59
	v_mul_f32_e32 v60, 0xbfb8aa3b, v60
	v_mul_f32_e32 v61, 0xbfb8aa3b, v61
	v_mul_f32_e32 v54, 0xbfb8aa3b, v54
	v_mul_f32_e32 v55, 0xbfb8aa3b, v55
	v_mul_f32_e32 v56, 0xbfb8aa3b, v56
	v_mul_f32_e32 v57, 0xbfb8aa3b, v57
	v_mul_f32_e32 v50, 0xbfb8aa3b, v50
	v_mul_f32_e32 v51, 0xbfb8aa3b, v51
	v_mul_f32_e32 v52, 0xbfb8aa3b, v52
	v_mul_f32_e32 v53, 0xbfb8aa3b, v53
	v_exp_f32_e32 v62, v62
	v_exp_f32_e32 v63, v63
	v_exp_f32_e32 v64, v64
	v_exp_f32_e32 v65, v65
	v_exp_f32_e32 v58, v58
	v_exp_f32_e32 v59, v59
	v_exp_f32_e32 v60, v60
	v_exp_f32_e32 v61, v61
	v_exp_f32_e32 v54, v54
	v_exp_f32_e32 v55, v55
	v_exp_f32_e32 v56, v56
	v_exp_f32_e32 v57, v57
	v_exp_f32_e32 v50, v50
	v_exp_f32_e32 v51, v51
	v_exp_f32_e32 v52, v52
	v_exp_f32_e32 v53, v53
	v_add_f32_e32 v62, 1.0, v62
	v_add_f32_e32 v63, 1.0, v63
	v_add_f32_e32 v64, 1.0, v64
	v_add_f32_e32 v65, 1.0, v65
	v_add_f32_e32 v58, 1.0, v58
	v_add_f32_e32 v59, 1.0, v59
	v_add_f32_e32 v60, 1.0, v60
	v_add_f32_e32 v61, 1.0, v61
	v_add_f32_e32 v54, 1.0, v54
	v_add_f32_e32 v55, 1.0, v55
	v_add_f32_e32 v56, 1.0, v56
	v_add_f32_e32 v57, 1.0, v57
	v_add_f32_e32 v50, 1.0, v50
	v_add_f32_e32 v51, 1.0, v51
	v_add_f32_e32 v52, 1.0, v52
	v_add_f32_e32 v53, 1.0, v53
	v_rcp_f32_e32 v62, v62
	v_rcp_f32_e32 v63, v63
	v_rcp_f32_e32 v64, v64
	v_rcp_f32_e32 v65, v65
	v_rcp_f32_e32 v58, v58
	v_rcp_f32_e32 v59, v59
	v_rcp_f32_e32 v60, v60
	v_rcp_f32_e32 v61, v61
	v_rcp_f32_e32 v54, v54
	v_rcp_f32_e32 v55, v55
	v_rcp_f32_e32 v56, v56
	v_rcp_f32_e32 v57, v57
	v_rcp_f32_e32 v50, v50
	v_rcp_f32_e32 v51, v51
	v_rcp_f32_e32 v52, v52
	v_rcp_f32_e32 v53, v53
	s_waitcnt vmcnt(12)
	v_add_u32_e32 v203, 0x40000, v194
	v_lshlrev_b32_e32 v210, 16, v130
	v_and_b32_e32 v211, 0xffff0000, v130
	v_lshlrev_b32_e32 v212, 16, v131
	v_and_b32_e32 v213, 0xffff0000, v131
	v_lshlrev_b32_e32 v214, 16, v132
	v_and_b32_e32 v215, 0xffff0000, v132
	v_lshlrev_b32_e32 v216, 16, v133
	v_and_b32_e32 v217, 0xffff0000, v133
	v_pk_mul_f32 v[210:211], v[250:251], v[210:211] op_sel_hi:[0,1]
	v_pk_mul_f32 v[212:213], v[250:251], v[212:213] op_sel_hi:[0,1]
	v_pk_mul_f32 v[214:215], v[250:251], v[214:215] op_sel_hi:[0,1]
	v_pk_mul_f32 v[216:217], v[250:251], v[216:217] op_sel_hi:[0,1]
	v_pk_mul_f32 v[210:211], v[62:63], v[210:211]
	v_pk_mul_f32 v[212:213], v[64:65], v[212:213]
	v_pk_mul_f32 v[214:215], v[58:59], v[214:215]
	v_pk_mul_f32 v[216:217], v[60:61], v[216:217]
	v_cvt_pk_bf16_f32 v130, v210, v211
	v_cvt_pk_bf16_f32 v131, v212, v213
	v_cvt_pk_bf16_f32 v132, v214, v215
	v_cvt_pk_bf16_f32 v133, v216, v217
	global_store_dwordx4 v203, v[130:133], s[16:17]
	v_lshlrev_b32_e32 v210, 16, v134
	v_and_b32_e32 v211, 0xffff0000, v134
	v_lshlrev_b32_e32 v212, 16, v135
	v_and_b32_e32 v213, 0xffff0000, v135
	v_lshlrev_b32_e32 v214, 16, v136
	v_and_b32_e32 v215, 0xffff0000, v136
	v_lshlrev_b32_e32 v216, 16, v137
	v_and_b32_e32 v217, 0xffff0000, v137
	v_pk_mul_f32 v[210:211], v[250:251], v[210:211] op_sel_hi:[0,1]
	v_pk_mul_f32 v[212:213], v[250:251], v[212:213] op_sel_hi:[0,1]
	v_pk_mul_f32 v[214:215], v[250:251], v[214:215] op_sel_hi:[0,1]
	v_pk_mul_f32 v[216:217], v[250:251], v[216:217] op_sel_hi:[0,1]
	v_pk_mul_f32 v[210:211], v[54:55], v[210:211]
	v_pk_mul_f32 v[212:213], v[56:57], v[212:213]
	v_pk_mul_f32 v[214:215], v[50:51], v[214:215]
	v_pk_mul_f32 v[216:217], v[52:53], v[216:217]
	v_cvt_pk_bf16_f32 v134, v210, v211
	v_cvt_pk_bf16_f32 v135, v212, v213
	v_cvt_pk_bf16_f32 v136, v214, v215
	v_cvt_pk_bf16_f32 v137, v216, v217
	global_store_dwordx4 v203, v[134:137], s[16:17] offset:256
	ds_read_b32 v205, v195 offset:576
	ds_read_b32 v250, v195 offset:4672
	s_waitcnt lgkmcnt(0)
	v_cndmask_b32_e64 v250, 1.0, v250, s[38:39]
	v_mul_f32_e32 v46, v46, v205
	v_mul_f32_e32 v47, v47, v205
	v_mul_f32_e32 v48, v48, v205
	v_mul_f32_e32 v49, v49, v205
	v_mul_f32_e32 v42, v42, v205
	v_mul_f32_e32 v43, v43, v205
	v_mul_f32_e32 v44, v44, v205
	v_mul_f32_e32 v45, v45, v205
	v_mul_f32_e32 v38, v38, v205
	v_mul_f32_e32 v39, v39, v205
	v_mul_f32_e32 v40, v40, v205
	v_mul_f32_e32 v41, v41, v205
	v_mul_f32_e32 v34, v34, v205
	v_mul_f32_e32 v35, v35, v205
	v_mul_f32_e32 v36, v36, v205
	v_mul_f32_e32 v37, v37, v205
	v_mul_f32_e32 v46, 0xbfb8aa3b, v46
	v_mul_f32_e32 v47, 0xbfb8aa3b, v47
	v_mul_f32_e32 v48, 0xbfb8aa3b, v48
	v_mul_f32_e32 v49, 0xbfb8aa3b, v49
	v_mul_f32_e32 v42, 0xbfb8aa3b, v42
	v_mul_f32_e32 v43, 0xbfb8aa3b, v43
	v_mul_f32_e32 v44, 0xbfb8aa3b, v44
	v_mul_f32_e32 v45, 0xbfb8aa3b, v45
	v_mul_f32_e32 v38, 0xbfb8aa3b, v38
	v_mul_f32_e32 v39, 0xbfb8aa3b, v39
	v_mul_f32_e32 v40, 0xbfb8aa3b, v40
	v_mul_f32_e32 v41, 0xbfb8aa3b, v41
	v_mul_f32_e32 v34, 0xbfb8aa3b, v34
	v_mul_f32_e32 v35, 0xbfb8aa3b, v35
	v_mul_f32_e32 v36, 0xbfb8aa3b, v36
	v_mul_f32_e32 v37, 0xbfb8aa3b, v37
	v_exp_f32_e32 v46, v46
	v_exp_f32_e32 v47, v47
	v_exp_f32_e32 v48, v48
	v_exp_f32_e32 v49, v49
	v_exp_f32_e32 v42, v42
	v_exp_f32_e32 v43, v43
	v_exp_f32_e32 v44, v44
	v_exp_f32_e32 v45, v45
	v_exp_f32_e32 v38, v38
	v_exp_f32_e32 v39, v39
	v_exp_f32_e32 v40, v40
	v_exp_f32_e32 v41, v41
	v_exp_f32_e32 v34, v34
	v_exp_f32_e32 v35, v35
	v_exp_f32_e32 v36, v36
	v_exp_f32_e32 v37, v37
	v_add_f32_e32 v46, 1.0, v46
	v_add_f32_e32 v47, 1.0, v47
	v_add_f32_e32 v48, 1.0, v48
	v_add_f32_e32 v49, 1.0, v49
	v_add_f32_e32 v42, 1.0, v42
	v_add_f32_e32 v43, 1.0, v43
	v_add_f32_e32 v44, 1.0, v44
	v_add_f32_e32 v45, 1.0, v45
	v_add_f32_e32 v38, 1.0, v38
	v_add_f32_e32 v39, 1.0, v39
	v_add_f32_e32 v40, 1.0, v40
	v_add_f32_e32 v41, 1.0, v41
	v_add_f32_e32 v34, 1.0, v34
	v_add_f32_e32 v35, 1.0, v35
	v_add_f32_e32 v36, 1.0, v36
	v_add_f32_e32 v37, 1.0, v37
	v_rcp_f32_e32 v46, v46
	v_rcp_f32_e32 v47, v47
	v_rcp_f32_e32 v48, v48
	v_rcp_f32_e32 v49, v49
	v_rcp_f32_e32 v42, v42
	v_rcp_f32_e32 v43, v43
	v_rcp_f32_e32 v44, v44
	v_rcp_f32_e32 v45, v45
	v_rcp_f32_e32 v38, v38
	v_rcp_f32_e32 v39, v39
	v_rcp_f32_e32 v40, v40
	v_rcp_f32_e32 v41, v41
	v_rcp_f32_e32 v34, v34
	v_rcp_f32_e32 v35, v35
	v_rcp_f32_e32 v36, v36
	v_rcp_f32_e32 v37, v37
	s_waitcnt vmcnt(10)
; __device__ __forceinline__ u32x4 pack8(f32x4 a, f32x4 b) { u32x4 w; w.x = cvt_pk_bf16(a[0], a[1]); w.y = cvt_pk_bf16(a[2], a[3]); w.z = cvt_pk_bf16(b[0], b[1]); w.w = cvt_pk_bf16(b[2], b[3]); return w; }
; __device__ __forceinline__ void unpack8(u32x4 w, f32x4& a, f32x4& b) { a = (f32x4){bflo(w.x), bfhi(w.x), bflo(w.y), bfhi(w.y)}; b = (f32x4){bflo(w.z), bfhi(w.z), bflo(w.w), bfhi(w.w)}; }
; __device__ __forceinline__ float sigmoidf_(float x) { return __builtin_amdgcn_rcpf(1.f + __builtin_amdgcn_exp2f(-1.4426950408889634f * x)); }
;     __device__ __forceinline__ void operator()(AccRef acc, const MUnit& u, int wr, int wc, int fr, int fq) const {
;     ...
;             EPI_ROWS_BEGIN
;                 const float r = rsl[row & 255]; const float ts = (n == 2) ? rsl[1024 + (row & 255)] : 1.f;
; #pragma unroll
;                 for (int bj = 0; bj < 2; ++bj) {
;                     const size_t off = (size_t)row * 1024 + col0 + bj * 128;
;                     f32x4 t0, t1; unpack8(tq[ai][m][bj], t0, t1); t0 = t0 * ts; t1 = t1 * ts;
;                     f32x4 g0 = acc[ai][bj][m][0] * r, g1 = acc[ai][bj][m][1] * r;
; #pragma unroll
;                     for (int e = 0; e < 4; ++e) { g0[e] = sigmoidf_(g0[e]) * t0[e]; g1[e] = sigmoidf_(g1[e]) * t1[e]; }
;                     if (n > 0) { f32x4 p0, p1; unpack8(*(const u32x4*)(mb + off), p0, p1); g0 += p0; g1 += p1; }
;                     *(u32x4*)(mb + off) = pack8(g0, g1);
	v_add_u32_e32 v203, 0x48000, v194
	v_lshlrev_b32_e32 v210, 16, v146
	v_and_b32_e32 v211, 0xffff0000, v146
	v_lshlrev_b32_e32 v212, 16, v147
	v_and_b32_e32 v213, 0xffff0000, v147
	v_lshlrev_b32_e32 v214, 16, v148
	v_and_b32_e32 v215, 0xffff0000, v148
	v_lshlrev_b32_e32 v216, 16, v149
	v_and_b32_e32 v217, 0xffff0000, v149
	v_pk_mul_f32 v[210:211], v[250:251], v[210:211] op_sel_hi:[0,1]
	v_pk_mul_f32 v[212:213], v[250:251], v[212:213] op_sel_hi:[0,1]
	v_pk_mul_f32 v[214:215], v[250:251], v[214:215] op_sel_hi:[0,1]
	v_pk_mul_f32 v[216:217], v[250:251], v[216:217] op_sel_hi:[0,1]
	v_pk_mul_f32 v[210:211], v[46:47], v[210:211]
	v_pk_mul_f32 v[212:213], v[48:49], v[212:213]
	v_pk_mul_f32 v[214:215], v[42:43], v[214:215]
	v_pk_mul_f32 v[216:217], v[44:45], v[216:217]
	v_cvt_pk_bf16_f32 v146, v210, v211
	v_cvt_pk_bf16_f32 v147, v212, v213
	v_cvt_pk_bf16_f32 v148, v214, v215
	v_cvt_pk_bf16_f32 v149, v216, v217
	global_store_dwordx4 v203, v[146:149], s[16:17]
	v_lshlrev_b32_e32 v210, 16, v150
	v_and_b32_e32 v211, 0xffff0000, v150
	v_lshlrev_b32_e32 v212, 16, v151
	v_and_b32_e32 v213, 0xffff0000, v151
	v_lshlrev_b32_e32 v214, 16, v152
	v_and_b32_e32 v215, 0xffff0000, v152
	v_lshlrev_b32_e32 v216, 16, v153
	v_and_b32_e32 v217, 0xffff0000, v153
	v_pk_mul_f32 v[210:211], v[250:251], v[210:211] op_sel_hi:[0,1]
	v_pk_mul_f32 v[212:213], v[250:251], v[212:213] op_sel_hi:[0,1]
	v_pk_mul_f32 v[214:215], v[250:251], v[214:215] op_sel_hi:[0,1]
	v_pk_mul_f32 v[216:217], v[250:251], v[216:217] op_sel_hi:[0,1]
	v_pk_mul_f32 v[210:211], v[38:39], v[210:211]
	v_pk_mul_f32 v[212:213], v[40:41], v[212:213]
	v_pk_mul_f32 v[214:215], v[34:35], v[214:215]
	v_pk_mul_f32 v[216:217], v[36:37], v[216:217]
	v_cvt_pk_bf16_f32 v150, v210, v211
	v_cvt_pk_bf16_f32 v151, v212, v213
	v_cvt_pk_bf16_f32 v152, v214, v215
	v_cvt_pk_bf16_f32 v153, v216, v217
	global_store_dwordx4 v203, v[150:153], s[16:17] offset:256
	ds_read_b32 v205, v195 offset:640
	ds_read_b32 v250, v195 offset:4736
	s_waitcnt lgkmcnt(0)
	v_cndmask_b32_e64 v250, 1.0, v250, s[38:39]
	v_mul_f32_e32 v30, v30, v205
	v_mul_f32_e32 v31, v31, v205
	v_mul_f32_e32 v32, v32, v205
	v_mul_f32_e32 v33, v33, v205
	v_mul_f32_e32 v26, v26, v205
	v_mul_f32_e32 v27, v27, v205
	v_mul_f32_e32 v28, v28, v205
	v_mul_f32_e32 v29, v29, v205
	v_mul_f32_e32 v22, v22, v205
	v_mul_f32_e32 v23, v23, v205
	v_mul_f32_e32 v24, v24, v205
	v_mul_f32_e32 v25, v25, v205
	v_mul_f32_e32 v18, v18, v205
	v_mul_f32_e32 v19, v19, v205
	v_mul_f32_e32 v20, v20, v205
	v_mul_f32_e32 v21, v21, v205
	v_mul_f32_e32 v30, 0xbfb8aa3b, v30
	v_mul_f32_e32 v31, 0xbfb8aa3b, v31
	v_mul_f32_e32 v32, 0xbfb8aa3b, v32
	v_mul_f32_e32 v33, 0xbfb8aa3b, v33
	v_mul_f32_e32 v26, 0xbfb8aa3b, v26
	v_mul_f32_e32 v27, 0xbfb8aa3b, v27
	v_mul_f32_e32 v28, 0xbfb8aa3b, v28
	v_mul_f32_e32 v29, 0xbfb8aa3b, v29
	v_mul_f32_e32 v22, 0xbfb8aa3b, v22
	v_mul_f32_e32 v23, 0xbfb8aa3b, v23
	v_mul_f32_e32 v24, 0xbfb8aa3b, v24
	v_mul_f32_e32 v25, 0xbfb8aa3b, v25
	v_mul_f32_e32 v18, 0xbfb8aa3b, v18
	v_mul_f32_e32 v19, 0xbfb8aa3b, v19
	v_mul_f32_e32 v20, 0xbfb8aa3b, v20
	v_mul_f32_e32 v21, 0xbfb8aa3b, v21
	v_exp_f32_e32 v30, v30
	v_exp_f32_e32 v31, v31
	v_exp_f32_e32 v32, v32
	v_exp_f32_e32 v33, v33
	v_exp_f32_e32 v26, v26
	v_exp_f32_e32 v27, v27
	v_exp_f32_e32 v28, v28
	v_exp_f32_e32 v29, v29
	v_exp_f32_e32 v22, v22
	v_exp_f32_e32 v23, v23
	v_exp_f32_e32 v24, v24
	v_exp_f32_e32 v25, v25
	v_exp_f32_e32 v18, v18
	v_exp_f32_e32 v19, v19
	v_exp_f32_e32 v20, v20
	v_exp_f32_e32 v21, v21
	v_add_f32_e32 v30, 1.0, v30
	v_add_f32_e32 v31, 1.0, v31
	v_add_f32_e32 v32, 1.0, v32
	v_add_f32_e32 v33, 1.0, v33
	v_add_f32_e32 v26, 1.0, v26
	v_add_f32_e32 v27, 1.0, v27
	v_add_f32_e32 v28, 1.0, v28
	v_add_f32_e32 v29, 1.0, v29
	v_add_f32_e32 v22, 1.0, v22
	v_add_f32_e32 v23, 1.0, v23
	v_add_f32_e32 v24, 1.0, v24
	v_add_f32_e32 v25, 1.0, v25
	v_add_f32_e32 v18, 1.0, v18
	v_add_f32_e32 v19, 1.0, v19
	v_add_f32_e32 v20, 1.0, v20
	v_add_f32_e32 v21, 1.0, v21
	v_rcp_f32_e32 v30, v30
	v_rcp_f32_e32 v31, v31
	v_rcp_f32_e32 v32, v32
	v_rcp_f32_e32 v33, v33
	v_rcp_f32_e32 v26, v26
	v_rcp_f32_e32 v27, v27
	v_rcp_f32_e32 v28, v28
	v_rcp_f32_e32 v29, v29
	v_rcp_f32_e32 v22, v22
	v_rcp_f32_e32 v23, v23
	v_rcp_f32_e32 v24, v24
	v_rcp_f32_e32 v25, v25
	v_rcp_f32_e32 v18, v18
	v_rcp_f32_e32 v19, v19
	v_rcp_f32_e32 v20, v20
	v_rcp_f32_e32 v21, v21
	s_waitcnt vmcnt(8)
	v_add_u32_e32 v203, 0x50000, v194
	v_lshlrev_b32_e32 v210, 16, v162
	v_and_b32_e32 v211, 0xffff0000, v162
	v_lshlrev_b32_e32 v212, 16, v163
	v_and_b32_e32 v213, 0xffff0000, v163
	v_lshlrev_b32_e32 v214, 16, v164
	v_and_b32_e32 v215, 0xffff0000, v164
	v_lshlrev_b32_e32 v216, 16, v165
	v_and_b32_e32 v217, 0xffff0000, v165
	v_pk_mul_f32 v[210:211], v[250:251], v[210:211] op_sel_hi:[0,1]
	v_pk_mul_f32 v[212:213], v[250:251], v[212:213] op_sel_hi:[0,1]
	v_pk_mul_f32 v[214:215], v[250:251], v[214:215] op_sel_hi:[0,1]
	v_pk_mul_f32 v[216:217], v[250:251], v[216:217] op_sel_hi:[0,1]
	v_pk_mul_f32 v[210:211], v[30:31], v[210:211]
	v_pk_mul_f32 v[212:213], v[32:33], v[212:213]
	v_pk_mul_f32 v[214:215], v[26:27], v[214:215]
	v_pk_mul_f32 v[216:217], v[28:29], v[216:217]
	v_cvt_pk_bf16_f32 v162, v210, v211
	v_cvt_pk_bf16_f32 v163, v212, v213
	v_cvt_pk_bf16_f32 v164, v214, v215
	v_cvt_pk_bf16_f32 v165, v216, v217
	global_store_dwordx4 v203, v[162:165], s[16:17]
	v_lshlrev_b32_e32 v210, 16, v166
	v_and_b32_e32 v211, 0xffff0000, v166
	v_lshlrev_b32_e32 v212, 16, v167
	v_and_b32_e32 v213, 0xffff0000, v167
	v_lshlrev_b32_e32 v214, 16, v168
	v_and_b32_e32 v215, 0xffff0000, v168
	v_lshlrev_b32_e32 v216, 16, v169
	v_and_b32_e32 v217, 0xffff0000, v169
	v_pk_mul_f32 v[210:211], v[250:251], v[210:211] op_sel_hi:[0,1]
	v_pk_mul_f32 v[212:213], v[250:251], v[212:213] op_sel_hi:[0,1]
	v_pk_mul_f32 v[214:215], v[250:251], v[214:215] op_sel_hi:[0,1]
	v_pk_mul_f32 v[216:217], v[250:251], v[216:217] op_sel_hi:[0,1]
	v_pk_mul_f32 v[210:211], v[22:23], v[210:211]
	v_pk_mul_f32 v[212:213], v[24:25], v[212:213]
	v_pk_mul_f32 v[214:215], v[18:19], v[214:215]
	v_pk_mul_f32 v[216:217], v[20:21], v[216:217]
	v_cvt_pk_bf16_f32 v166, v210, v211
	v_cvt_pk_bf16_f32 v167, v212, v213
	v_cvt_pk_bf16_f32 v168, v214, v215
	v_cvt_pk_bf16_f32 v169, v216, v217
	global_store_dwordx4 v203, v[166:169], s[16:17] offset:256
	ds_read_b32 v205, v195 offset:704
	ds_read_b32 v250, v195 offset:4800
	s_waitcnt lgkmcnt(0)
; #define LAS __attribute__((address_space(3)))
; __device__ __forceinline__ u32x4 pack8(f32x4 a, f32x4 b) { u32x4 w; w.x = cvt_pk_bf16(a[0], a[1]); w.y = cvt_pk_bf16(a[2], a[3]); w.z = cvt_pk_bf16(b[0], b[1]); w.w = cvt_pk_bf16(b[2], b[3]); return w; }
; __device__ __forceinline__ void unpack8(u32x4 w, f32x4& a, f32x4& b) { a = (f32x4){bflo(w.x), bfhi(w.x), bflo(w.y), bfhi(w.y)}; b = (f32x4){bflo(w.z), bfhi(w.z), bflo(w.w), bfhi(w.w)}; }
; __device__ __forceinline__ float sigmoidf_(float x) { return __builtin_amdgcn_rcpf(1.f + __builtin_amdgcn_exp2f(-1.4426950408889634f * x)); }
;     __device__ __forceinline__ void operator()(AccRef acc, const MUnit& u, int wr, int wc, int fr, int fq) const {
;     ...
;             const LAS float* rsl = (const LAS float*)(lds_rs + RSL_OFF) + (u.ui >> 3) * 256;
;             u32x4 tq[2][4][2];
; #pragma unroll
;             for (int ai = 0; ai < 2; ++ai)
; #pragma unroll
;                 for (int m = 0; m < 4; ++m)
; #pragma unroll
;                     for (int bj = 0; bj < 2; ++bj) tq[ai][m][bj] = *(const u32x4*)(tn + (size_t)(u.pm * 256 + ai * 128 + wr * 64 + m * 16 + fr) * 1024 + col0 + bj * 128);
;             EPI_ROWS_BEGIN
;                 const float r = rsl[row & 255]; const float ts = (n == 2) ? rsl[1024 + (row & 255)] : 1.f;
; #pragma unroll
;                 for (int bj = 0; bj < 2; ++bj) {
;                     const size_t off = (size_t)row * 1024 + col0 + bj * 128;
;                     f32x4 t0, t1; unpack8(tq[ai][m][bj], t0, t1); t0 = t0 * ts; t1 = t1 * ts;
;                     f32x4 g0 = acc[ai][bj][m][0] * r, g1 = acc[ai][bj][m][1] * r;
; #pragma unroll
;                     for (int e = 0; e < 4; ++e) { g0[e] = sigmoidf_(g0[e]) * t0[e]; g1[e] = sigmoidf_(g1[e]) * t1[e]; }
;                     if (n > 0) { f32x4 p0, p1; unpack8(*(const u32x4*)(mb + off), p0, p1); g0 += p0; g1 += p1; }
;                     *(u32x4*)(mb + off) = pack8(g0, g1);
	v_cndmask_b32_e64 v250, 1.0, v250, s[38:39]
	v_mul_f32_e32 v14, v14, v205
	v_mul_f32_e32 v15, v15, v205
	v_mul_f32_e32 v16, v16, v205
	v_mul_f32_e32 v17, v17, v205
	v_mul_f32_e32 v10, v10, v205
	v_mul_f32_e32 v11, v11, v205
	v_mul_f32_e32 v12, v12, v205
	v_mul_f32_e32 v13, v13, v205
	v_mul_f32_e32 v6, v6, v205
	v_mul_f32_e32 v7, v7, v205
	v_mul_f32_e32 v8, v8, v205
	v_mul_f32_e32 v9, v9, v205
	v_mul_f32_e32 v2, v2, v205
	v_mul_f32_e32 v3, v3, v205
	v_mul_f32_e32 v4, v4, v205
	v_mul_f32_e32 v5, v5, v205
	v_mul_f32_e32 v14, 0xbfb8aa3b, v14
	v_mul_f32_e32 v15, 0xbfb8aa3b, v15
	v_mul_f32_e32 v16, 0xbfb8aa3b, v16
	v_mul_f32_e32 v17, 0xbfb8aa3b, v17
	v_mul_f32_e32 v10, 0xbfb8aa3b, v10
	v_mul_f32_e32 v11, 0xbfb8aa3b, v11
	v_mul_f32_e32 v12, 0xbfb8aa3b, v12
	v_mul_f32_e32 v13, 0xbfb8aa3b, v13
	v_mul_f32_e32 v6, 0xbfb8aa3b, v6
	v_mul_f32_e32 v7, 0xbfb8aa3b, v7
	v_mul_f32_e32 v8, 0xbfb8aa3b, v8
	v_mul_f32_e32 v9, 0xbfb8aa3b, v9
	v_mul_f32_e32 v2, 0xbfb8aa3b, v2
	v_mul_f32_e32 v3, 0xbfb8aa3b, v3
	v_mul_f32_e32 v4, 0xbfb8aa3b, v4
	v_mul_f32_e32 v5, 0xbfb8aa3b, v5
	v_exp_f32_e32 v14, v14
	v_exp_f32_e32 v15, v15
	v_exp_f32_e32 v16, v16
	v_exp_f32_e32 v17, v17
	v_exp_f32_e32 v10, v10
	v_exp_f32_e32 v11, v11
	v_exp_f32_e32 v12, v12
	v_exp_f32_e32 v13, v13
	v_exp_f32_e32 v6, v6
	v_exp_f32_e32 v7, v7
	v_exp_f32_e32 v8, v8
	v_exp_f32_e32 v9, v9
	v_exp_f32_e32 v2, v2
	v_exp_f32_e32 v3, v3
	v_exp_f32_e32 v4, v4
	v_exp_f32_e32 v5, v5
	v_add_f32_e32 v14, 1.0, v14
	v_add_f32_e32 v15, 1.0, v15
	v_add_f32_e32 v16, 1.0, v16
	v_add_f32_e32 v17, 1.0, v17
	v_add_f32_e32 v10, 1.0, v10
	v_add_f32_e32 v11, 1.0, v11
	v_add_f32_e32 v12, 1.0, v12
	v_add_f32_e32 v13, 1.0, v13
	v_add_f32_e32 v6, 1.0, v6
	v_add_f32_e32 v7, 1.0, v7
	v_add_f32_e32 v8, 1.0, v8
	v_add_f32_e32 v9, 1.0, v9
	v_add_f32_e32 v2, 1.0, v2
	v_add_f32_e32 v3, 1.0, v3
	v_add_f32_e32 v4, 1.0, v4
	v_add_f32_e32 v5, 1.0, v5
	v_rcp_f32_e32 v14, v14
	v_rcp_f32_e32 v15, v15
	v_rcp_f32_e32 v16, v16
	v_rcp_f32_e32 v17, v17
	v_rcp_f32_e32 v10, v10
	v_rcp_f32_e32 v11, v11
	v_rcp_f32_e32 v12, v12
	v_rcp_f32_e32 v13, v13
	v_rcp_f32_e32 v6, v6
	v_rcp_f32_e32 v7, v7
	v_rcp_f32_e32 v8, v8
	v_rcp_f32_e32 v9, v9
	v_rcp_f32_e32 v2, v2
	v_rcp_f32_e32 v3, v3
	v_rcp_f32_e32 v4, v4
	v_rcp_f32_e32 v5, v5
	s_waitcnt vmcnt(6)
	v_add_u32_e32 v203, 0x58000, v194
	v_lshlrev_b32_e32 v210, 16, v178
	v_and_b32_e32 v211, 0xffff0000, v178
	v_lshlrev_b32_e32 v212, 16, v179
	v_and_b32_e32 v213, 0xffff0000, v179
	v_lshlrev_b32_e32 v214, 16, v180
	v_and_b32_e32 v215, 0xffff0000, v180
	v_lshlrev_b32_e32 v216, 16, v181
	v_and_b32_e32 v217, 0xffff0000, v181
	v_pk_mul_f32 v[210:211], v[250:251], v[210:211] op_sel_hi:[0,1]
	v_pk_mul_f32 v[212:213], v[250:251], v[212:213] op_sel_hi:[0,1]
	v_pk_mul_f32 v[214:215], v[250:251], v[214:215] op_sel_hi:[0,1]
	v_pk_mul_f32 v[216:217], v[250:251], v[216:217] op_sel_hi:[0,1]
	v_pk_mul_f32 v[210:211], v[14:15], v[210:211]
	v_pk_mul_f32 v[212:213], v[16:17], v[212:213]
	v_pk_mul_f32 v[214:215], v[10:11], v[214:215]
	v_pk_mul_f32 v[216:217], v[12:13], v[216:217]
	v_cvt_pk_bf16_f32 v178, v210, v211
	v_cvt_pk_bf16_f32 v179, v212, v213
	v_cvt_pk_bf16_f32 v180, v214, v215
	v_cvt_pk_bf16_f32 v181, v216, v217
	global_store_dwordx4 v203, v[178:181], s[16:17]
	v_lshlrev_b32_e32 v210, 16, v182
	v_and_b32_e32 v211, 0xffff0000, v182
	v_lshlrev_b32_e32 v212, 16, v183
	v_and_b32_e32 v213, 0xffff0000, v183
	v_lshlrev_b32_e32 v214, 16, v184
	v_and_b32_e32 v215, 0xffff0000, v184
	v_lshlrev_b32_e32 v216, 16, v185
	v_and_b32_e32 v217, 0xffff0000, v185
	v_pk_mul_f32 v[210:211], v[250:251], v[210:211] op_sel_hi:[0,1]
	v_pk_mul_f32 v[212:213], v[250:251], v[212:213] op_sel_hi:[0,1]
	v_pk_mul_f32 v[214:215], v[250:251], v[214:215] op_sel_hi:[0,1]
	v_pk_mul_f32 v[216:217], v[250:251], v[216:217] op_sel_hi:[0,1]
	v_pk_mul_f32 v[210:211], v[6:7], v[210:211]
	v_pk_mul_f32 v[212:213], v[8:9], v[212:213]
	v_pk_mul_f32 v[214:215], v[2:3], v[214:215]
	v_pk_mul_f32 v[216:217], v[4:5], v[216:217]
	v_cvt_pk_bf16_f32 v182, v210, v211
	v_cvt_pk_bf16_f32 v183, v212, v213
	v_cvt_pk_bf16_f32 v184, v214, v215
	v_cvt_pk_bf16_f32 v185, v216, v217
	global_store_dwordx4 v203, v[182:185], s[16:17] offset:256
	s_branch .LBB0_1385
.Lgate_mb:
	s_lshl_b32 s6, s68, 19
	s_lshl_b32 s23, s67, 9
	s_add_u32 s6, s6, s23
	v_lshlrev_b32_e32 v0, 11, v237
	v_lshl_add_u32 v0, v247, 1, v0
	v_add_u32_e32 v194, s6, v0
	v_mov_b32_e32 v0, v194
	global_load_dwordx4 v[130:133], v0, s[0:1]
	global_load_dwordx4 v[134:137], v0, s[0:1] offset:256
	global_load_dwordx4 v[138:141], v0, s[16:17]
	global_load_dwordx4 v[142:145], v0, s[16:17] offset:256
	v_add_u32_e32 v0, 0x8000, v194
	global_load_dwordx4 v[146:149], v0, s[0:1]
	global_load_dwordx4 v[150:153], v0, s[0:1] offset:256
	global_load_dwordx4 v[154:157], v0, s[16:17]
	global_load_dwordx4 v[158:161], v0, s[16:17] offset:256
	v_add_u32_e32 v0, 0x10000, v194
	global_load_dwordx4 v[162:165], v0, s[0:1]
	global_load_dwordx4 v[166:169], v0, s[0:1] offset:256
	global_load_dwordx4 v[170:173], v0, s[16:17]
	global_load_dwordx4 v[174:177], v0, s[16:17] offset:256
	v_add_u32_e32 v0, 0x18000, v194
	global_load_dwordx4 v[178:181], v0, s[0:1]
	global_load_dwordx4 v[182:185], v0, s[0:1] offset:256
	global_load_dwordx4 v[186:189], v0, s[16:17]
	global_load_dwordx4 v[190:193], v0, s[16:17] offset:256
	s_lshl_b32 s6, s65, 7
	s_and_b32 s6, s6, 0xfffffc00
	s_add_i32 s23, s6, 0x21000
	v_lshl_add_u32 v195, v237, 2, s23
	ds_read_b32 v205, v195 offset:0
	ds_read_b32 v250, v195 offset:4096
	s_waitcnt lgkmcnt(0)
; __device__ __forceinline__ u32x4 pack8(f32x4 a, f32x4 b) { u32x4 w; w.x = cvt_pk_bf16(a[0], a[1]); w.y = cvt_pk_bf16(a[2], a[3]); w.z = cvt_pk_bf16(b[0], b[1]); w.w = cvt_pk_bf16(b[2], b[3]); return w; }
; __device__ __forceinline__ void unpack8(u32x4 w, f32x4& a, f32x4& b) { a = (f32x4){bflo(w.x), bfhi(w.x), bflo(w.y), bfhi(w.y)}; b = (f32x4){bflo(w.z), bfhi(w.z), bflo(w.w), bfhi(w.w)}; }
; __device__ __forceinline__ float sigmoidf_(float x) { return __builtin_amdgcn_rcpf(1.f + __builtin_amdgcn_exp2f(-1.4426950408889634f * x)); }
;     __device__ __forceinline__ void operator()(AccRef acc, const MUnit& u, int wr, int wc, int fr, int fq) const {
;     ...
;             EPI_ROWS_BEGIN
;                 const float r = rsl[row & 255]; const float ts = (n == 2) ? rsl[1024 + (row & 255)] : 1.f;
; #pragma unroll
;                 for (int bj = 0; bj < 2; ++bj) {
;                     const size_t off = (size_t)row * 1024 + col0 + bj * 128;
;                     f32x4 t0, t1; unpack8(tq[ai][m][bj], t0, t1); t0 = t0 * ts; t1 = t1 * ts;
;                     f32x4 g0 = acc[ai][bj][m][0] * r, g1 = acc[ai][bj][m][1] * r;
; #pragma unroll
;                     for (int e = 0; e < 4; ++e) { g0[e] = sigmoidf_(g0[e]) * t0[e]; g1[e] = sigmoidf_(g1[e]) * t1[e]; }
;                     if (n > 0) { f32x4 p0, p1; unpack8(*(const u32x4*)(mb + off), p0, p1); g0 += p0; g1 += p1; }
;                     *(u32x4*)(mb + off) = pack8(g0, g1);
	v_cndmask_b32_e64 v250, 1.0, v250, s[38:39]
	v_mul_f32_e32 v126, v126, v205
	v_mul_f32_e32 v127, v127, v205
	v_mul_f32_e32 v128, v128, v205
	v_mul_f32_e32 v129, v129, v205
	v_mul_f32_e32 v122, v122, v205
	v_mul_f32_e32 v123, v123, v205
	v_mul_f32_e32 v124, v124, v205
	v_mul_f32_e32 v125, v125, v205
	v_mul_f32_e32 v118, v118, v205
	v_mul_f32_e32 v119, v119, v205
	v_mul_f32_e32 v120, v120, v205
	v_mul_f32_e32 v121, v121, v205
	v_mul_f32_e32 v114, v114, v205
	v_mul_f32_e32 v115, v115, v205
	v_mul_f32_e32 v116, v116, v205
	v_mul_f32_e32 v117, v117, v205
	v_mul_f32_e32 v126, 0xbfb8aa3b, v126
	v_mul_f32_e32 v127, 0xbfb8aa3b, v127
	v_mul_f32_e32 v128, 0xbfb8aa3b, v128
	v_mul_f32_e32 v129, 0xbfb8aa3b, v129
	v_mul_f32_e32 v122, 0xbfb8aa3b, v122
	v_mul_f32_e32 v123, 0xbfb8aa3b, v123
	v_mul_f32_e32 v124, 0xbfb8aa3b, v124
	v_mul_f32_e32 v125, 0xbfb8aa3b, v125
	v_mul_f32_e32 v118, 0xbfb8aa3b, v118
	v_mul_f32_e32 v119, 0xbfb8aa3b, v119
	v_mul_f32_e32 v120, 0xbfb8aa3b, v120
	v_mul_f32_e32 v121, 0xbfb8aa3b, v121
	v_mul_f32_e32 v114, 0xbfb8aa3b, v114
	v_mul_f32_e32 v115, 0xbfb8aa3b, v115
	v_mul_f32_e32 v116, 0xbfb8aa3b, v116
	v_mul_f32_e32 v117, 0xbfb8aa3b, v117
	v_exp_f32_e32 v126, v126
	v_exp_f32_e32 v127, v127
	v_exp_f32_e32 v128, v128
	v_exp_f32_e32 v129, v129
	v_exp_f32_e32 v122, v122
	v_exp_f32_e32 v123, v123
	v_exp_f32_e32 v124, v124
	v_exp_f32_e32 v125, v125
	v_exp_f32_e32 v118, v118
	v_exp_f32_e32 v119, v119
	v_exp_f32_e32 v120, v120
	v_exp_f32_e32 v121, v121
	v_exp_f32_e32 v114, v114
	v_exp_f32_e32 v115, v115
	v_exp_f32_e32 v116, v116
	v_exp_f32_e32 v117, v117
	v_add_f32_e32 v126, 1.0, v126
	v_add_f32_e32 v127, 1.0, v127
	v_add_f32_e32 v128, 1.0, v128
	v_add_f32_e32 v129, 1.0, v129
	v_add_f32_e32 v122, 1.0, v122
	v_add_f32_e32 v123, 1.0, v123
	v_add_f32_e32 v124, 1.0, v124
	v_add_f32_e32 v125, 1.0, v125
	v_add_f32_e32 v118, 1.0, v118
	v_add_f32_e32 v119, 1.0, v119
	v_add_f32_e32 v120, 1.0, v120
	v_add_f32_e32 v121, 1.0, v121
	v_add_f32_e32 v114, 1.0, v114
	v_add_f32_e32 v115, 1.0, v115
	v_add_f32_e32 v116, 1.0, v116
	v_add_f32_e32 v117, 1.0, v117
	v_rcp_f32_e32 v126, v126
	v_rcp_f32_e32 v127, v127
	v_rcp_f32_e32 v128, v128
	v_rcp_f32_e32 v129, v129
	v_rcp_f32_e32 v122, v122
	v_rcp_f32_e32 v123, v123
	v_rcp_f32_e32 v124, v124
	v_rcp_f32_e32 v125, v125
	v_rcp_f32_e32 v118, v118
	v_rcp_f32_e32 v119, v119
	v_rcp_f32_e32 v120, v120
	v_rcp_f32_e32 v121, v121
	v_rcp_f32_e32 v114, v114
	v_rcp_f32_e32 v115, v115
	v_rcp_f32_e32 v116, v116
	v_rcp_f32_e32 v117, v117
	s_waitcnt vmcnt(12)
	v_mov_b32_e32 v203, v194
	v_lshlrev_b32_e32 v210, 16, v130
	v_and_b32_e32 v211, 0xffff0000, v130
	v_lshlrev_b32_e32 v212, 16, v131
	v_and_b32_e32 v213, 0xffff0000, v131
	v_lshlrev_b32_e32 v214, 16, v132
	v_and_b32_e32 v215, 0xffff0000, v132
	v_lshlrev_b32_e32 v216, 16, v133
	v_and_b32_e32 v217, 0xffff0000, v133
	v_pk_mul_f32 v[210:211], v[250:251], v[210:211] op_sel_hi:[0,1]
	v_pk_mul_f32 v[212:213], v[250:251], v[212:213] op_sel_hi:[0,1]
	v_pk_mul_f32 v[214:215], v[250:251], v[214:215] op_sel_hi:[0,1]
	v_pk_mul_f32 v[216:217], v[250:251], v[216:217] op_sel_hi:[0,1]
	v_pk_mul_f32 v[210:211], v[126:127], v[210:211]
	v_pk_mul_f32 v[212:213], v[128:129], v[212:213]
	v_pk_mul_f32 v[214:215], v[122:123], v[214:215]
	v_pk_mul_f32 v[216:217], v[124:125], v[216:217]
	v_lshlrev_b32_e32 v218, 16, v138
	v_and_b32_e32 v219, 0xffff0000, v138
	v_lshlrev_b32_e32 v220, 16, v139
	v_and_b32_e32 v221, 0xffff0000, v139
	v_lshlrev_b32_e32 v198, 16, v140
	v_and_b32_e32 v199, 0xffff0000, v140
	v_lshlrev_b32_e32 v200, 16, v141
	v_and_b32_e32 v201, 0xffff0000, v141
	v_pk_add_f32 v[210:211], v[210:211], v[218:219]
	v_pk_add_f32 v[212:213], v[212:213], v[220:221]
	v_pk_add_f32 v[214:215], v[214:215], v[198:199]
	v_pk_add_f32 v[216:217], v[216:217], v[200:201]
	v_cvt_pk_bf16_f32 v130, v210, v211
	v_cvt_pk_bf16_f32 v131, v212, v213
	v_cvt_pk_bf16_f32 v132, v214, v215
	v_cvt_pk_bf16_f32 v133, v216, v217
	global_store_dwordx4 v203, v[130:133], s[16:17]
	v_lshlrev_b32_e32 v210, 16, v134
	v_and_b32_e32 v211, 0xffff0000, v134
	v_lshlrev_b32_e32 v212, 16, v135
	v_and_b32_e32 v213, 0xffff0000, v135
	v_lshlrev_b32_e32 v214, 16, v136
	v_and_b32_e32 v215, 0xffff0000, v136
	v_lshlrev_b32_e32 v216, 16, v137
	v_and_b32_e32 v217, 0xffff0000, v137
	v_pk_mul_f32 v[210:211], v[250:251], v[210:211] op_sel_hi:[0,1]
	v_pk_mul_f32 v[212:213], v[250:251], v[212:213] op_sel_hi:[0,1]
	v_pk_mul_f32 v[214:215], v[250:251], v[214:215] op_sel_hi:[0,1]
	v_pk_mul_f32 v[216:217], v[250:251], v[216:217] op_sel_hi:[0,1]
	v_pk_mul_f32 v[210:211], v[118:119], v[210:211]
	v_pk_mul_f32 v[212:213], v[120:121], v[212:213]
	v_pk_mul_f32 v[214:215], v[114:115], v[214:215]
	v_pk_mul_f32 v[216:217], v[116:117], v[216:217]
	v_lshlrev_b32_e32 v218, 16, v142
	v_and_b32_e32 v219, 0xffff0000, v142
	v_lshlrev_b32_e32 v220, 16, v143
	v_and_b32_e32 v221, 0xffff0000, v143
	v_lshlrev_b32_e32 v198, 16, v144
	v_and_b32_e32 v199, 0xffff0000, v144
	v_lshlrev_b32_e32 v200, 16, v145
	v_and_b32_e32 v201, 0xffff0000, v145
	v_pk_add_f32 v[210:211], v[210:211], v[218:219]
	v_pk_add_f32 v[212:213], v[212:213], v[220:221]
	v_pk_add_f32 v[214:215], v[214:215], v[198:199]
	v_pk_add_f32 v[216:217], v[216:217], v[200:201]
	v_cvt_pk_bf16_f32 v134, v210, v211
	v_cvt_pk_bf16_f32 v135, v212, v213
	v_cvt_pk_bf16_f32 v136, v214, v215
	v_cvt_pk_bf16_f32 v137, v216, v217
	global_store_dwordx4 v203, v[134:137], s[16:17] offset:256
	s_nop 1
	v_add_u32_e32 v0, 0x40000, v194
	global_load_dwordx4 v[130:133], v0, s[0:1]
	global_load_dwordx4 v[134:137], v0, s[0:1] offset:256
	global_load_dwordx4 v[138:141], v0, s[16:17]
	global_load_dwordx4 v[142:145], v0, s[16:17] offset:256
	ds_read_b32 v205, v195 offset:64
	ds_read_b32 v250, v195 offset:4160
	s_waitcnt lgkmcnt(0)
; __device__ __forceinline__ u32x4 pack8(f32x4 a, f32x4 b) { u32x4 w; w.x = cvt_pk_bf16(a[0], a[1]); w.y = cvt_pk_bf16(a[2], a[3]); w.z = cvt_pk_bf16(b[0], b[1]); w.w = cvt_pk_bf16(b[2], b[3]); return w; }
; __device__ __forceinline__ void unpack8(u32x4 w, f32x4& a, f32x4& b) { a = (f32x4){bflo(w.x), bfhi(w.x), bflo(w.y), bfhi(w.y)}; b = (f32x4){bflo(w.z), bfhi(w.z), bflo(w.w), bfhi(w.w)}; }
; __device__ __forceinline__ float sigmoidf_(float x) { return __builtin_amdgcn_rcpf(1.f + __builtin_amdgcn_exp2f(-1.4426950408889634f * x)); }
;     __device__ __forceinline__ void operator()(AccRef acc, const MUnit& u, int wr, int wc, int fr, int fq) const {
;     ...
;             EPI_ROWS_BEGIN
;                 const float r = rsl[row & 255]; const float ts = (n == 2) ? rsl[1024 + (row & 255)] : 1.f;
; #pragma unroll
;                 for (int bj = 0; bj < 2; ++bj) {
;                     const size_t off = (size_t)row * 1024 + col0 + bj * 128;
;                     f32x4 t0, t1; unpack8(tq[ai][m][bj], t0, t1); t0 = t0 * ts; t1 = t1 * ts;
;                     f32x4 g0 = acc[ai][bj][m][0] * r, g1 = acc[ai][bj][m][1] * r;
; #pragma unroll
;                     for (int e = 0; e < 4; ++e) { g0[e] = sigmoidf_(g0[e]) * t0[e]; g1[e] = sigmoidf_(g1[e]) * t1[e]; }
;                     if (n > 0) { f32x4 p0, p1; unpack8(*(const u32x4*)(mb + off), p0, p1); g0 += p0; g1 += p1; }
;                     *(u32x4*)(mb + off) = pack8(g0, g1);
	v_cndmask_b32_e64 v250, 1.0, v250, s[38:39]
	v_mul_f32_e32 v110, v110, v205
	v_mul_f32_e32 v111, v111, v205
	v_mul_f32_e32 v112, v112, v205
	v_mul_f32_e32 v113, v113, v205
	v_mul_f32_e32 v106, v106, v205
	v_mul_f32_e32 v107, v107, v205
	v_mul_f32_e32 v108, v108, v205
	v_mul_f32_e32 v109, v109, v205
	v_mul_f32_e32 v102, v102, v205
	v_mul_f32_e32 v103, v103, v205
	v_mul_f32_e32 v104, v104, v205
	v_mul_f32_e32 v105, v105, v205
	v_mul_f32_e32 v98, v98, v205
	v_mul_f32_e32 v99, v99, v205
	v_mul_f32_e32 v100, v100, v205
	v_mul_f32_e32 v101, v101, v205
	v_mul_f32_e32 v110, 0xbfb8aa3b, v110
	v_mul_f32_e32 v111, 0xbfb8aa3b, v111
	v_mul_f32_e32 v112, 0xbfb8aa3b, v112
	v_mul_f32_e32 v113, 0xbfb8aa3b, v113
	v_mul_f32_e32 v106, 0xbfb8aa3b, v106
	v_mul_f32_e32 v107, 0xbfb8aa3b, v107
	v_mul_f32_e32 v108, 0xbfb8aa3b, v108
	v_mul_f32_e32 v109, 0xbfb8aa3b, v109
	v_mul_f32_e32 v102, 0xbfb8aa3b, v102
	v_mul_f32_e32 v103, 0xbfb8aa3b, v103
	v_mul_f32_e32 v104, 0xbfb8aa3b, v104
	v_mul_f32_e32 v105, 0xbfb8aa3b, v105
	v_mul_f32_e32 v98, 0xbfb8aa3b, v98
	v_mul_f32_e32 v99, 0xbfb8aa3b, v99
	v_mul_f32_e32 v100, 0xbfb8aa3b, v100
	v_mul_f32_e32 v101, 0xbfb8aa3b, v101
	v_exp_f32_e32 v110, v110
	v_exp_f32_e32 v111, v111
	v_exp_f32_e32 v112, v112
	v_exp_f32_e32 v113, v113
	v_exp_f32_e32 v106, v106
	v_exp_f32_e32 v107, v107
	v_exp_f32_e32 v108, v108
	v_exp_f32_e32 v109, v109
	v_exp_f32_e32 v102, v102
	v_exp_f32_e32 v103, v103
	v_exp_f32_e32 v104, v104
	v_exp_f32_e32 v105, v105
	v_exp_f32_e32 v98, v98
	v_exp_f32_e32 v99, v99
	v_exp_f32_e32 v100, v100
	v_exp_f32_e32 v101, v101
	v_add_f32_e32 v110, 1.0, v110
	v_add_f32_e32 v111, 1.0, v111
	v_add_f32_e32 v112, 1.0, v112
	v_add_f32_e32 v113, 1.0, v113
	v_add_f32_e32 v106, 1.0, v106
	v_add_f32_e32 v107, 1.0, v107
	v_add_f32_e32 v108, 1.0, v108
	v_add_f32_e32 v109, 1.0, v109
	v_add_f32_e32 v102, 1.0, v102
	v_add_f32_e32 v103, 1.0, v103
	v_add_f32_e32 v104, 1.0, v104
	v_add_f32_e32 v105, 1.0, v105
	v_add_f32_e32 v98, 1.0, v98
	v_add_f32_e32 v99, 1.0, v99
	v_add_f32_e32 v100, 1.0, v100
	v_add_f32_e32 v101, 1.0, v101
	v_rcp_f32_e32 v110, v110
	v_rcp_f32_e32 v111, v111
	v_rcp_f32_e32 v112, v112
	v_rcp_f32_e32 v113, v113
	v_rcp_f32_e32 v106, v106
	v_rcp_f32_e32 v107, v107
	v_rcp_f32_e32 v108, v108
	v_rcp_f32_e32 v109, v109
	v_rcp_f32_e32 v102, v102
	v_rcp_f32_e32 v103, v103
	v_rcp_f32_e32 v104, v104
	v_rcp_f32_e32 v105, v105
	v_rcp_f32_e32 v98, v98
	v_rcp_f32_e32 v99, v99
	v_rcp_f32_e32 v100, v100
	v_rcp_f32_e32 v101, v101
	s_waitcnt vmcnt(14)
	v_add_u32_e32 v203, 0x8000, v194
	v_lshlrev_b32_e32 v210, 16, v146
	v_and_b32_e32 v211, 0xffff0000, v146
	v_lshlrev_b32_e32 v212, 16, v147
	v_and_b32_e32 v213, 0xffff0000, v147
	v_lshlrev_b32_e32 v214, 16, v148
	v_and_b32_e32 v215, 0xffff0000, v148
	v_lshlrev_b32_e32 v216, 16, v149
	v_and_b32_e32 v217, 0xffff0000, v149
	v_pk_mul_f32 v[210:211], v[250:251], v[210:211] op_sel_hi:[0,1]
	v_pk_mul_f32 v[212:213], v[250:251], v[212:213] op_sel_hi:[0,1]
	v_pk_mul_f32 v[214:215], v[250:251], v[214:215] op_sel_hi:[0,1]
	v_pk_mul_f32 v[216:217], v[250:251], v[216:217] op_sel_hi:[0,1]
	v_pk_mul_f32 v[210:211], v[110:111], v[210:211]
	v_pk_mul_f32 v[212:213], v[112:113], v[212:213]
	v_pk_mul_f32 v[214:215], v[106:107], v[214:215]
	v_pk_mul_f32 v[216:217], v[108:109], v[216:217]
	v_lshlrev_b32_e32 v218, 16, v154
	v_and_b32_e32 v219, 0xffff0000, v154
	v_lshlrev_b32_e32 v220, 16, v155
	v_and_b32_e32 v221, 0xffff0000, v155
	v_lshlrev_b32_e32 v198, 16, v156
	v_and_b32_e32 v199, 0xffff0000, v156
	v_lshlrev_b32_e32 v200, 16, v157
	v_and_b32_e32 v201, 0xffff0000, v157
	v_pk_add_f32 v[210:211], v[210:211], v[218:219]
	v_pk_add_f32 v[212:213], v[212:213], v[220:221]
	v_pk_add_f32 v[214:215], v[214:215], v[198:199]
	v_pk_add_f32 v[216:217], v[216:217], v[200:201]
	v_cvt_pk_bf16_f32 v146, v210, v211
	v_cvt_pk_bf16_f32 v147, v212, v213
	v_cvt_pk_bf16_f32 v148, v214, v215
	v_cvt_pk_bf16_f32 v149, v216, v217
	global_store_dwordx4 v203, v[146:149], s[16:17]
	v_lshlrev_b32_e32 v210, 16, v150
	v_and_b32_e32 v211, 0xffff0000, v150
	v_lshlrev_b32_e32 v212, 16, v151
	v_and_b32_e32 v213, 0xffff0000, v151
	v_lshlrev_b32_e32 v214, 16, v152
	v_and_b32_e32 v215, 0xffff0000, v152
	v_lshlrev_b32_e32 v216, 16, v153
	v_and_b32_e32 v217, 0xffff0000, v153
	v_pk_mul_f32 v[210:211], v[250:251], v[210:211] op_sel_hi:[0,1]
	v_pk_mul_f32 v[212:213], v[250:251], v[212:213] op_sel_hi:[0,1]
	v_pk_mul_f32 v[214:215], v[250:251], v[214:215] op_sel_hi:[0,1]
	v_pk_mul_f32 v[216:217], v[250:251], v[216:217] op_sel_hi:[0,1]
	v_pk_mul_f32 v[210:211], v[102:103], v[210:211]
	v_pk_mul_f32 v[212:213], v[104:105], v[212:213]
	v_pk_mul_f32 v[214:215], v[98:99], v[214:215]
	v_pk_mul_f32 v[216:217], v[100:101], v[216:217]
	v_lshlrev_b32_e32 v218, 16, v158
	v_and_b32_e32 v219, 0xffff0000, v158
	v_lshlrev_b32_e32 v220, 16, v159
	v_and_b32_e32 v221, 0xffff0000, v159
	v_lshlrev_b32_e32 v198, 16, v160
	v_and_b32_e32 v199, 0xffff0000, v160
	v_lshlrev_b32_e32 v200, 16, v161
	v_and_b32_e32 v201, 0xffff0000, v161
	v_pk_add_f32 v[210:211], v[210:211], v[218:219]
	v_pk_add_f32 v[212:213], v[212:213], v[220:221]
	v_pk_add_f32 v[214:215], v[214:215], v[198:199]
	v_pk_add_f32 v[216:217], v[216:217], v[200:201]
	v_cvt_pk_bf16_f32 v150, v210, v211
	v_cvt_pk_bf16_f32 v151, v212, v213
	v_cvt_pk_bf16_f32 v152, v214, v215
	v_cvt_pk_bf16_f32 v153, v216, v217
	global_store_dwordx4 v203, v[150:153], s[16:17] offset:256
	s_nop 1
	v_add_u32_e32 v0, 0x48000, v194
	global_load_dwordx4 v[146:149], v0, s[0:1]
	global_load_dwordx4 v[150:153], v0, s[0:1] offset:256
	global_load_dwordx4 v[154:157], v0, s[16:17]
	global_load_dwordx4 v[158:161], v0, s[16:17] offset:256
	ds_read_b32 v205, v195 offset:128
	ds_read_b32 v250, v195 offset:4224
	s_waitcnt lgkmcnt(0)
; __device__ __forceinline__ u32x4 pack8(f32x4 a, f32x4 b) { u32x4 w; w.x = cvt_pk_bf16(a[0], a[1]); w.y = cvt_pk_bf16(a[2], a[3]); w.z = cvt_pk_bf16(b[0], b[1]); w.w = cvt_pk_bf16(b[2], b[3]); return w; }
; __device__ __forceinline__ void unpack8(u32x4 w, f32x4& a, f32x4& b) { a = (f32x4){bflo(w.x), bfhi(w.x), bflo(w.y), bfhi(w.y)}; b = (f32x4){bflo(w.z), bfhi(w.z), bflo(w.w), bfhi(w.w)}; }
; __device__ __forceinline__ float sigmoidf_(float x) { return __builtin_amdgcn_rcpf(1.f + __builtin_amdgcn_exp2f(-1.4426950408889634f * x)); }
;     __device__ __forceinline__ void operator()(AccRef acc, const MUnit& u, int wr, int wc, int fr, int fq) const {
;     ...
;             EPI_ROWS_BEGIN
;                 const float r = rsl[row & 255]; const float ts = (n == 2) ? rsl[1024 + (row & 255)] : 1.f;
; #pragma unroll
;                 for (int bj = 0; bj < 2; ++bj) {
;                     const size_t off = (size_t)row * 1024 + col0 + bj * 128;
;                     f32x4 t0, t1; unpack8(tq[ai][m][bj], t0, t1); t0 = t0 * ts; t1 = t1 * ts;
;                     f32x4 g0 = acc[ai][bj][m][0] * r, g1 = acc[ai][bj][m][1] * r;
; #pragma unroll
;                     for (int e = 0; e < 4; ++e) { g0[e] = sigmoidf_(g0[e]) * t0[e]; g1[e] = sigmoidf_(g1[e]) * t1[e]; }
;                     if (n > 0) { f32x4 p0, p1; unpack8(*(const u32x4*)(mb + off), p0, p1); g0 += p0; g1 += p1; }
;                     *(u32x4*)(mb + off) = pack8(g0, g1);
	v_cndmask_b32_e64 v250, 1.0, v250, s[38:39]
	v_mul_f32_e32 v94, v94, v205
	v_mul_f32_e32 v95, v95, v205
	v_mul_f32_e32 v96, v96, v205
	v_mul_f32_e32 v97, v97, v205
	v_mul_f32_e32 v90, v90, v205
	v_mul_f32_e32 v91, v91, v205
	v_mul_f32_e32 v92, v92, v205
	v_mul_f32_e32 v93, v93, v205
	v_mul_f32_e32 v86, v86, v205
	v_mul_f32_e32 v87, v87, v205
	v_mul_f32_e32 v88, v88, v205
	v_mul_f32_e32 v89, v89, v205
	v_mul_f32_e32 v82, v82, v205
	v_mul_f32_e32 v83, v83, v205
	v_mul_f32_e32 v84, v84, v205
	v_mul_f32_e32 v85, v85, v205
	v_mul_f32_e32 v94, 0xbfb8aa3b, v94
	v_mul_f32_e32 v95, 0xbfb8aa3b, v95
	v_mul_f32_e32 v96, 0xbfb8aa3b, v96
	v_mul_f32_e32 v97, 0xbfb8aa3b, v97
	v_mul_f32_e32 v90, 0xbfb8aa3b, v90
	v_mul_f32_e32 v91, 0xbfb8aa3b, v91
	v_mul_f32_e32 v92, 0xbfb8aa3b, v92
	v_mul_f32_e32 v93, 0xbfb8aa3b, v93
	v_mul_f32_e32 v86, 0xbfb8aa3b, v86
	v_mul_f32_e32 v87, 0xbfb8aa3b, v87
	v_mul_f32_e32 v88, 0xbfb8aa3b, v88
	v_mul_f32_e32 v89, 0xbfb8aa3b, v89
	v_mul_f32_e32 v82, 0xbfb8aa3b, v82
	v_mul_f32_e32 v83, 0xbfb8aa3b, v83
	v_mul_f32_e32 v84, 0xbfb8aa3b, v84
	v_mul_f32_e32 v85, 0xbfb8aa3b, v85
	v_exp_f32_e32 v94, v94
	v_exp_f32_e32 v95, v95
	v_exp_f32_e32 v96, v96
	v_exp_f32_e32 v97, v97
	v_exp_f32_e32 v90, v90
	v_exp_f32_e32 v91, v91
	v_exp_f32_e32 v92, v92
	v_exp_f32_e32 v93, v93
	v_exp_f32_e32 v86, v86
	v_exp_f32_e32 v87, v87
	v_exp_f32_e32 v88, v88
	v_exp_f32_e32 v89, v89
	v_exp_f32_e32 v82, v82
	v_exp_f32_e32 v83, v83
	v_exp_f32_e32 v84, v84
	v_exp_f32_e32 v85, v85
	v_add_f32_e32 v94, 1.0, v94
	v_add_f32_e32 v95, 1.0, v95
	v_add_f32_e32 v96, 1.0, v96
	v_add_f32_e32 v97, 1.0, v97
	v_add_f32_e32 v90, 1.0, v90
	v_add_f32_e32 v91, 1.0, v91
	v_add_f32_e32 v92, 1.0, v92
	v_add_f32_e32 v93, 1.0, v93
	v_add_f32_e32 v86, 1.0, v86
	v_add_f32_e32 v87, 1.0, v87
	v_add_f32_e32 v88, 1.0, v88
	v_add_f32_e32 v89, 1.0, v89
	v_add_f32_e32 v82, 1.0, v82
	v_add_f32_e32 v83, 1.0, v83
	v_add_f32_e32 v84, 1.0, v84
	v_add_f32_e32 v85, 1.0, v85
	v_rcp_f32_e32 v94, v94
	v_rcp_f32_e32 v95, v95
	v_rcp_f32_e32 v96, v96
	v_rcp_f32_e32 v97, v97
	v_rcp_f32_e32 v90, v90
	v_rcp_f32_e32 v91, v91
	v_rcp_f32_e32 v92, v92
	v_rcp_f32_e32 v93, v93
	v_rcp_f32_e32 v86, v86
	v_rcp_f32_e32 v87, v87
	v_rcp_f32_e32 v88, v88
	v_rcp_f32_e32 v89, v89
	v_rcp_f32_e32 v82, v82
	v_rcp_f32_e32 v83, v83
	v_rcp_f32_e32 v84, v84
	v_rcp_f32_e32 v85, v85
	s_waitcnt vmcnt(16)
	v_add_u32_e32 v203, 0x10000, v194
	v_lshlrev_b32_e32 v210, 16, v162
	v_and_b32_e32 v211, 0xffff0000, v162
	v_lshlrev_b32_e32 v212, 16, v163
	v_and_b32_e32 v213, 0xffff0000, v163
	v_lshlrev_b32_e32 v214, 16, v164
	v_and_b32_e32 v215, 0xffff0000, v164
	v_lshlrev_b32_e32 v216, 16, v165
	v_and_b32_e32 v217, 0xffff0000, v165
	v_pk_mul_f32 v[210:211], v[250:251], v[210:211] op_sel_hi:[0,1]
	v_pk_mul_f32 v[212:213], v[250:251], v[212:213] op_sel_hi:[0,1]
	v_pk_mul_f32 v[214:215], v[250:251], v[214:215] op_sel_hi:[0,1]
	v_pk_mul_f32 v[216:217], v[250:251], v[216:217] op_sel_hi:[0,1]
	v_pk_mul_f32 v[210:211], v[94:95], v[210:211]
	v_pk_mul_f32 v[212:213], v[96:97], v[212:213]
	v_pk_mul_f32 v[214:215], v[90:91], v[214:215]
	v_pk_mul_f32 v[216:217], v[92:93], v[216:217]
	v_lshlrev_b32_e32 v218, 16, v170
	v_and_b32_e32 v219, 0xffff0000, v170
	v_lshlrev_b32_e32 v220, 16, v171
	v_and_b32_e32 v221, 0xffff0000, v171
	v_lshlrev_b32_e32 v198, 16, v172
	v_and_b32_e32 v199, 0xffff0000, v172
	v_lshlrev_b32_e32 v200, 16, v173
	v_and_b32_e32 v201, 0xffff0000, v173
	v_pk_add_f32 v[210:211], v[210:211], v[218:219]
	v_pk_add_f32 v[212:213], v[212:213], v[220:221]
	v_pk_add_f32 v[214:215], v[214:215], v[198:199]
	v_pk_add_f32 v[216:217], v[216:217], v[200:201]
	v_cvt_pk_bf16_f32 v162, v210, v211
	v_cvt_pk_bf16_f32 v163, v212, v213
	v_cvt_pk_bf16_f32 v164, v214, v215
	v_cvt_pk_bf16_f32 v165, v216, v217
	global_store_dwordx4 v203, v[162:165], s[16:17]
	v_lshlrev_b32_e32 v210, 16, v166
	v_and_b32_e32 v211, 0xffff0000, v166
	v_lshlrev_b32_e32 v212, 16, v167
	v_and_b32_e32 v213, 0xffff0000, v167
	v_lshlrev_b32_e32 v214, 16, v168
	v_and_b32_e32 v215, 0xffff0000, v168
	v_lshlrev_b32_e32 v216, 16, v169
	v_and_b32_e32 v217, 0xffff0000, v169
	v_pk_mul_f32 v[210:211], v[250:251], v[210:211] op_sel_hi:[0,1]
	v_pk_mul_f32 v[212:213], v[250:251], v[212:213] op_sel_hi:[0,1]
	v_pk_mul_f32 v[214:215], v[250:251], v[214:215] op_sel_hi:[0,1]
	v_pk_mul_f32 v[216:217], v[250:251], v[216:217] op_sel_hi:[0,1]
	v_pk_mul_f32 v[210:211], v[86:87], v[210:211]
	v_pk_mul_f32 v[212:213], v[88:89], v[212:213]
	v_pk_mul_f32 v[214:215], v[82:83], v[214:215]
	v_pk_mul_f32 v[216:217], v[84:85], v[216:217]
	v_lshlrev_b32_e32 v218, 16, v174
	v_and_b32_e32 v219, 0xffff0000, v174
	v_lshlrev_b32_e32 v220, 16, v175
	v_and_b32_e32 v221, 0xffff0000, v175
	v_lshlrev_b32_e32 v198, 16, v176
	v_and_b32_e32 v199, 0xffff0000, v176
	v_lshlrev_b32_e32 v200, 16, v177
	v_and_b32_e32 v201, 0xffff0000, v177
	v_pk_add_f32 v[210:211], v[210:211], v[218:219]
	v_pk_add_f32 v[212:213], v[212:213], v[220:221]
	v_pk_add_f32 v[214:215], v[214:215], v[198:199]
	v_pk_add_f32 v[216:217], v[216:217], v[200:201]
	v_cvt_pk_bf16_f32 v166, v210, v211
	v_cvt_pk_bf16_f32 v167, v212, v213
	v_cvt_pk_bf16_f32 v168, v214, v215
	v_cvt_pk_bf16_f32 v169, v216, v217
	global_store_dwordx4 v203, v[166:169], s[16:17] offset:256
	s_nop 1
	v_add_u32_e32 v0, 0x50000, v194
	global_load_dwordx4 v[162:165], v0, s[0:1]
	global_load_dwordx4 v[166:169], v0, s[0:1] offset:256
	global_load_dwordx4 v[170:173], v0, s[16:17]
	global_load_dwordx4 v[174:177], v0, s[16:17] offset:256
	ds_read_b32 v205, v195 offset:192
	ds_read_b32 v250, v195 offset:4288
	s_waitcnt lgkmcnt(0)
; __device__ __forceinline__ u32x4 pack8(f32x4 a, f32x4 b) { u32x4 w; w.x = cvt_pk_bf16(a[0], a[1]); w.y = cvt_pk_bf16(a[2], a[3]); w.z = cvt_pk_bf16(b[0], b[1]); w.w = cvt_pk_bf16(b[2], b[3]); return w; }
; __device__ __forceinline__ void unpack8(u32x4 w, f32x4& a, f32x4& b) { a = (f32x4){bflo(w.x), bfhi(w.x), bflo(w.y), bfhi(w.y)}; b = (f32x4){bflo(w.z), bfhi(w.z), bflo(w.w), bfhi(w.w)}; }
; __device__ __forceinline__ float sigmoidf_(float x) { return __builtin_amdgcn_rcpf(1.f + __builtin_amdgcn_exp2f(-1.4426950408889634f * x)); }
;     __device__ __forceinline__ void operator()(AccRef acc, const MUnit& u, int wr, int wc, int fr, int fq) const {
;     ...
;             EPI_ROWS_BEGIN
;                 const float r = rsl[row & 255]; const float ts = (n == 2) ? rsl[1024 + (row & 255)] : 1.f;
; #pragma unroll
;                 for (int bj = 0; bj < 2; ++bj) {
;                     const size_t off = (size_t)row * 1024 + col0 + bj * 128;
;                     f32x4 t0, t1; unpack8(tq[ai][m][bj], t0, t1); t0 = t0 * ts; t1 = t1 * ts;
;                     f32x4 g0 = acc[ai][bj][m][0] * r, g1 = acc[ai][bj][m][1] * r;
; #pragma unroll
;                     for (int e = 0; e < 4; ++e) { g0[e] = sigmoidf_(g0[e]) * t0[e]; g1[e] = sigmoidf_(g1[e]) * t1[e]; }
;                     if (n > 0) { f32x4 p0, p1; unpack8(*(const u32x4*)(mb + off), p0, p1); g0 += p0; g1 += p1; }
;                     *(u32x4*)(mb + off) = pack8(g0, g1);
	v_cndmask_b32_e64 v250, 1.0, v250, s[38:39]
	v_mul_f32_e32 v78, v78, v205
	v_mul_f32_e32 v79, v79, v205
	v_mul_f32_e32 v80, v80, v205
	v_mul_f32_e32 v81, v81, v205
	v_mul_f32_e32 v74, v74, v205
	v_mul_f32_e32 v75, v75, v205
	v_mul_f32_e32 v76, v76, v205
	v_mul_f32_e32 v77, v77, v205
	v_mul_f32_e32 v70, v70, v205
	v_mul_f32_e32 v71, v71, v205
	v_mul_f32_e32 v72, v72, v205
	v_mul_f32_e32 v73, v73, v205
	v_mul_f32_e32 v66, v66, v205
	v_mul_f32_e32 v67, v67, v205
	v_mul_f32_e32 v68, v68, v205
	v_mul_f32_e32 v69, v69, v205
	v_mul_f32_e32 v78, 0xbfb8aa3b, v78
	v_mul_f32_e32 v79, 0xbfb8aa3b, v79
	v_mul_f32_e32 v80, 0xbfb8aa3b, v80
	v_mul_f32_e32 v81, 0xbfb8aa3b, v81
	v_mul_f32_e32 v74, 0xbfb8aa3b, v74
	v_mul_f32_e32 v75, 0xbfb8aa3b, v75
	v_mul_f32_e32 v76, 0xbfb8aa3b, v76
	v_mul_f32_e32 v77, 0xbfb8aa3b, v77
	v_mul_f32_e32 v70, 0xbfb8aa3b, v70
	v_mul_f32_e32 v71, 0xbfb8aa3b, v71
	v_mul_f32_e32 v72, 0xbfb8aa3b, v72
	v_mul_f32_e32 v73, 0xbfb8aa3b, v73
	v_mul_f32_e32 v66, 0xbfb8aa3b, v66
	v_mul_f32_e32 v67, 0xbfb8aa3b, v67
	v_mul_f32_e32 v68, 0xbfb8aa3b, v68
	v_mul_f32_e32 v69, 0xbfb8aa3b, v69
	v_exp_f32_e32 v78, v78
	v_exp_f32_e32 v79, v79
	v_exp_f32_e32 v80, v80
	v_exp_f32_e32 v81, v81
	v_exp_f32_e32 v74, v74
	v_exp_f32_e32 v75, v75
	v_exp_f32_e32 v76, v76
	v_exp_f32_e32 v77, v77
	v_exp_f32_e32 v70, v70
	v_exp_f32_e32 v71, v71
	v_exp_f32_e32 v72, v72
	v_exp_f32_e32 v73, v73
	v_exp_f32_e32 v66, v66
	v_exp_f32_e32 v67, v67
	v_exp_f32_e32 v68, v68
	v_exp_f32_e32 v69, v69
	v_add_f32_e32 v78, 1.0, v78
	v_add_f32_e32 v79, 1.0, v79
	v_add_f32_e32 v80, 1.0, v80
	v_add_f32_e32 v81, 1.0, v81
	v_add_f32_e32 v74, 1.0, v74
	v_add_f32_e32 v75, 1.0, v75
	v_add_f32_e32 v76, 1.0, v76
	v_add_f32_e32 v77, 1.0, v77
	v_add_f32_e32 v70, 1.0, v70
	v_add_f32_e32 v71, 1.0, v71
	v_add_f32_e32 v72, 1.0, v72
	v_add_f32_e32 v73, 1.0, v73
	v_add_f32_e32 v66, 1.0, v66
	v_add_f32_e32 v67, 1.0, v67
	v_add_f32_e32 v68, 1.0, v68
	v_add_f32_e32 v69, 1.0, v69
	v_rcp_f32_e32 v78, v78
	v_rcp_f32_e32 v79, v79
	v_rcp_f32_e32 v80, v80
	v_rcp_f32_e32 v81, v81
	v_rcp_f32_e32 v74, v74
	v_rcp_f32_e32 v75, v75
	v_rcp_f32_e32 v76, v76
	v_rcp_f32_e32 v77, v77
	v_rcp_f32_e32 v70, v70
	v_rcp_f32_e32 v71, v71
	v_rcp_f32_e32 v72, v72
	v_rcp_f32_e32 v73, v73
	v_rcp_f32_e32 v66, v66
	v_rcp_f32_e32 v67, v67
	v_rcp_f32_e32 v68, v68
	v_rcp_f32_e32 v69, v69
	s_waitcnt vmcnt(18)
	v_add_u32_e32 v203, 0x18000, v194
	v_lshlrev_b32_e32 v210, 16, v178
	v_and_b32_e32 v211, 0xffff0000, v178
	v_lshlrev_b32_e32 v212, 16, v179
	v_and_b32_e32 v213, 0xffff0000, v179
	v_lshlrev_b32_e32 v214, 16, v180
	v_and_b32_e32 v215, 0xffff0000, v180
	v_lshlrev_b32_e32 v216, 16, v181
	v_and_b32_e32 v217, 0xffff0000, v181
	v_pk_mul_f32 v[210:211], v[250:251], v[210:211] op_sel_hi:[0,1]
	v_pk_mul_f32 v[212:213], v[250:251], v[212:213] op_sel_hi:[0,1]
	v_pk_mul_f32 v[214:215], v[250:251], v[214:215] op_sel_hi:[0,1]
	v_pk_mul_f32 v[216:217], v[250:251], v[216:217] op_sel_hi:[0,1]
	v_pk_mul_f32 v[210:211], v[78:79], v[210:211]
	v_pk_mul_f32 v[212:213], v[80:81], v[212:213]
	v_pk_mul_f32 v[214:215], v[74:75], v[214:215]
	v_pk_mul_f32 v[216:217], v[76:77], v[216:217]
	v_lshlrev_b32_e32 v218, 16, v186
	v_and_b32_e32 v219, 0xffff0000, v186
	v_lshlrev_b32_e32 v220, 16, v187
	v_and_b32_e32 v221, 0xffff0000, v187
	v_lshlrev_b32_e32 v198, 16, v188
	v_and_b32_e32 v199, 0xffff0000, v188
	v_lshlrev_b32_e32 v200, 16, v189
	v_and_b32_e32 v201, 0xffff0000, v189
	v_pk_add_f32 v[210:211], v[210:211], v[218:219]
	v_pk_add_f32 v[212:213], v[212:213], v[220:221]
	v_pk_add_f32 v[214:215], v[214:215], v[198:199]
	v_pk_add_f32 v[216:217], v[216:217], v[200:201]
	v_cvt_pk_bf16_f32 v178, v210, v211
	v_cvt_pk_bf16_f32 v179, v212, v213
	v_cvt_pk_bf16_f32 v180, v214, v215
	v_cvt_pk_bf16_f32 v181, v216, v217
	global_store_dwordx4 v203, v[178:181], s[16:17]
	v_lshlrev_b32_e32 v210, 16, v182
	v_and_b32_e32 v211, 0xffff0000, v182
	v_lshlrev_b32_e32 v212, 16, v183
	v_and_b32_e32 v213, 0xffff0000, v183
	v_lshlrev_b32_e32 v214, 16, v184
	v_and_b32_e32 v215, 0xffff0000, v184
	v_lshlrev_b32_e32 v216, 16, v185
	v_and_b32_e32 v217, 0xffff0000, v185
	v_pk_mul_f32 v[210:211], v[250:251], v[210:211] op_sel_hi:[0,1]
	v_pk_mul_f32 v[212:213], v[250:251], v[212:213] op_sel_hi:[0,1]
	v_pk_mul_f32 v[214:215], v[250:251], v[214:215] op_sel_hi:[0,1]
	v_pk_mul_f32 v[216:217], v[250:251], v[216:217] op_sel_hi:[0,1]
	v_pk_mul_f32 v[210:211], v[70:71], v[210:211]
	v_pk_mul_f32 v[212:213], v[72:73], v[212:213]
	v_pk_mul_f32 v[214:215], v[66:67], v[214:215]
	v_pk_mul_f32 v[216:217], v[68:69], v[216:217]
	v_lshlrev_b32_e32 v218, 16, v190
	v_and_b32_e32 v219, 0xffff0000, v190
	v_lshlrev_b32_e32 v220, 16, v191
	v_and_b32_e32 v221, 0xffff0000, v191
	v_lshlrev_b32_e32 v198, 16, v192
	v_and_b32_e32 v199, 0xffff0000, v192
	v_lshlrev_b32_e32 v200, 16, v193
	v_and_b32_e32 v201, 0xffff0000, v193
	v_pk_add_f32 v[210:211], v[210:211], v[218:219]
	v_pk_add_f32 v[212:213], v[212:213], v[220:221]
	v_pk_add_f32 v[214:215], v[214:215], v[198:199]
	v_pk_add_f32 v[216:217], v[216:217], v[200:201]
	v_cvt_pk_bf16_f32 v182, v210, v211
	v_cvt_pk_bf16_f32 v183, v212, v213
	v_cvt_pk_bf16_f32 v184, v214, v215
	v_cvt_pk_bf16_f32 v185, v216, v217
	global_store_dwordx4 v203, v[182:185], s[16:17] offset:256
	s_nop 1
	v_add_u32_e32 v0, 0x58000, v194
	global_load_dwordx4 v[178:181], v0, s[0:1]
	global_load_dwordx4 v[182:185], v0, s[0:1] offset:256
	global_load_dwordx4 v[186:189], v0, s[16:17]
	global_load_dwordx4 v[190:193], v0, s[16:17] offset:256
	ds_read_b32 v205, v195 offset:512
	ds_read_b32 v250, v195 offset:4608
	s_waitcnt lgkmcnt(0)
; __device__ __forceinline__ u32x4 pack8(f32x4 a, f32x4 b) { u32x4 w; w.x = cvt_pk_bf16(a[0], a[1]); w.y = cvt_pk_bf16(a[2], a[3]); w.z = cvt_pk_bf16(b[0], b[1]); w.w = cvt_pk_bf16(b[2], b[3]); return w; }
; __device__ __forceinline__ void unpack8(u32x4 w, f32x4& a, f32x4& b) { a = (f32x4){bflo(w.x), bfhi(w.x), bflo(w.y), bfhi(w.y)}; b = (f32x4){bflo(w.z), bfhi(w.z), bflo(w.w), bfhi(w.w)}; }
; __device__ __forceinline__ float sigmoidf_(float x) { return __builtin_amdgcn_rcpf(1.f + __builtin_amdgcn_exp2f(-1.4426950408889634f * x)); }
;     __device__ __forceinline__ void operator()(AccRef acc, const MUnit& u, int wr, int wc, int fr, int fq) const {
;     ...
;             EPI_ROWS_BEGIN
;                 const float r = rsl[row & 255]; const float ts = (n == 2) ? rsl[1024 + (row & 255)] : 1.f;
; #pragma unroll
;                 for (int bj = 0; bj < 2; ++bj) {
;                     const size_t off = (size_t)row * 1024 + col0 + bj * 128;
;                     f32x4 t0, t1; unpack8(tq[ai][m][bj], t0, t1); t0 = t0 * ts; t1 = t1 * ts;
;                     f32x4 g0 = acc[ai][bj][m][0] * r, g1 = acc[ai][bj][m][1] * r;
; #pragma unroll
;                     for (int e = 0; e < 4; ++e) { g0[e] = sigmoidf_(g0[e]) * t0[e]; g1[e] = sigmoidf_(g1[e]) * t1[e]; }
;                     if (n > 0) { f32x4 p0, p1; unpack8(*(const u32x4*)(mb + off), p0, p1); g0 += p0; g1 += p1; }
;                     *(u32x4*)(mb + off) = pack8(g0, g1);
	v_cndmask_b32_e64 v250, 1.0, v250, s[38:39]
	v_mul_f32_e32 v62, v62, v205
	v_mul_f32_e32 v63, v63, v205
	v_mul_f32_e32 v64, v64, v205
	v_mul_f32_e32 v65, v65, v205
	v_mul_f32_e32 v58, v58, v205
	v_mul_f32_e32 v59, v59, v205
	v_mul_f32_e32 v60, v60, v205
	v_mul_f32_e32 v61, v61, v205
	v_mul_f32_e32 v54, v54, v205
	v_mul_f32_e32 v55, v55, v205
	v_mul_f32_e32 v56, v56, v205
	v_mul_f32_e32 v57, v57, v205
	v_mul_f32_e32 v50, v50, v205
	v_mul_f32_e32 v51, v51, v205
	v_mul_f32_e32 v52, v52, v205
	v_mul_f32_e32 v53, v53, v205
	v_mul_f32_e32 v62, 0xbfb8aa3b, v62
	v_mul_f32_e32 v63, 0xbfb8aa3b, v63
	v_mul_f32_e32 v64, 0xbfb8aa3b, v64
	v_mul_f32_e32 v65, 0xbfb8aa3b, v65
	v_mul_f32_e32 v58, 0xbfb8aa3b, v58
	v_mul_f32_e32 v59, 0xbfb8aa3b, v59
	v_mul_f32_e32 v60, 0xbfb8aa3b, v60
	v_mul_f32_e32 v61, 0xbfb8aa3b, v61
	v_mul_f32_e32 v54, 0xbfb8aa3b, v54
	v_mul_f32_e32 v55, 0xbfb8aa3b, v55
	v_mul_f32_e32 v56, 0xbfb8aa3b, v56
	v_mul_f32_e32 v57, 0xbfb8aa3b, v57
	v_mul_f32_e32 v50, 0xbfb8aa3b, v50
	v_mul_f32_e32 v51, 0xbfb8aa3b, v51
	v_mul_f32_e32 v52, 0xbfb8aa3b, v52
	v_mul_f32_e32 v53, 0xbfb8aa3b, v53
	v_exp_f32_e32 v62, v62
	v_exp_f32_e32 v63, v63
	v_exp_f32_e32 v64, v64
	v_exp_f32_e32 v65, v65
	v_exp_f32_e32 v58, v58
	v_exp_f32_e32 v59, v59
	v_exp_f32_e32 v60, v60
	v_exp_f32_e32 v61, v61
	v_exp_f32_e32 v54, v54
	v_exp_f32_e32 v55, v55
	v_exp_f32_e32 v56, v56
	v_exp_f32_e32 v57, v57
	v_exp_f32_e32 v50, v50
	v_exp_f32_e32 v51, v51
	v_exp_f32_e32 v52, v52
	v_exp_f32_e32 v53, v53
	v_add_f32_e32 v62, 1.0, v62
	v_add_f32_e32 v63, 1.0, v63
	v_add_f32_e32 v64, 1.0, v64
	v_add_f32_e32 v65, 1.0, v65
	v_add_f32_e32 v58, 1.0, v58
	v_add_f32_e32 v59, 1.0, v59
	v_add_f32_e32 v60, 1.0, v60
	v_add_f32_e32 v61, 1.0, v61
	v_add_f32_e32 v54, 1.0, v54
	v_add_f32_e32 v55, 1.0, v55
	v_add_f32_e32 v56, 1.0, v56
	v_add_f32_e32 v57, 1.0, v57
	v_add_f32_e32 v50, 1.0, v50
	v_add_f32_e32 v51, 1.0, v51
	v_add_f32_e32 v52, 1.0, v52
	v_add_f32_e32 v53, 1.0, v53
	v_rcp_f32_e32 v62, v62
	v_rcp_f32_e32 v63, v63
	v_rcp_f32_e32 v64, v64
	v_rcp_f32_e32 v65, v65
	v_rcp_f32_e32 v58, v58
	v_rcp_f32_e32 v59, v59
	v_rcp_f32_e32 v60, v60
	v_rcp_f32_e32 v61, v61
	v_rcp_f32_e32 v54, v54
	v_rcp_f32_e32 v55, v55
	v_rcp_f32_e32 v56, v56
	v_rcp_f32_e32 v57, v57
	v_rcp_f32_e32 v50, v50
	v_rcp_f32_e32 v51, v51
	v_rcp_f32_e32 v52, v52
	v_rcp_f32_e32 v53, v53
	s_waitcnt vmcnt(18)
	v_add_u32_e32 v203, 0x40000, v194
	v_lshlrev_b32_e32 v210, 16, v130
	v_and_b32_e32 v211, 0xffff0000, v130
	v_lshlrev_b32_e32 v212, 16, v131
	v_and_b32_e32 v213, 0xffff0000, v131
	v_lshlrev_b32_e32 v214, 16, v132
	v_and_b32_e32 v215, 0xffff0000, v132
	v_lshlrev_b32_e32 v216, 16, v133
	v_and_b32_e32 v217, 0xffff0000, v133
	v_pk_mul_f32 v[210:211], v[250:251], v[210:211] op_sel_hi:[0,1]
	v_pk_mul_f32 v[212:213], v[250:251], v[212:213] op_sel_hi:[0,1]
	v_pk_mul_f32 v[214:215], v[250:251], v[214:215] op_sel_hi:[0,1]
	v_pk_mul_f32 v[216:217], v[250:251], v[216:217] op_sel_hi:[0,1]
	v_pk_mul_f32 v[210:211], v[62:63], v[210:211]
	v_pk_mul_f32 v[212:213], v[64:65], v[212:213]
	v_pk_mul_f32 v[214:215], v[58:59], v[214:215]
	v_pk_mul_f32 v[216:217], v[60:61], v[216:217]
	v_lshlrev_b32_e32 v218, 16, v138
	v_and_b32_e32 v219, 0xffff0000, v138
	v_lshlrev_b32_e32 v220, 16, v139
	v_and_b32_e32 v221, 0xffff0000, v139
	v_lshlrev_b32_e32 v198, 16, v140
	v_and_b32_e32 v199, 0xffff0000, v140
	v_lshlrev_b32_e32 v200, 16, v141
	v_and_b32_e32 v201, 0xffff0000, v141
	v_pk_add_f32 v[210:211], v[210:211], v[218:219]
	v_pk_add_f32 v[212:213], v[212:213], v[220:221]
	v_pk_add_f32 v[214:215], v[214:215], v[198:199]
	v_pk_add_f32 v[216:217], v[216:217], v[200:201]
	v_cvt_pk_bf16_f32 v130, v210, v211
	v_cvt_pk_bf16_f32 v131, v212, v213
	v_cvt_pk_bf16_f32 v132, v214, v215
	v_cvt_pk_bf16_f32 v133, v216, v217
	global_store_dwordx4 v203, v[130:133], s[16:17]
	v_lshlrev_b32_e32 v210, 16, v134
	v_and_b32_e32 v211, 0xffff0000, v134
	v_lshlrev_b32_e32 v212, 16, v135
	v_and_b32_e32 v213, 0xffff0000, v135
	v_lshlrev_b32_e32 v214, 16, v136
	v_and_b32_e32 v215, 0xffff0000, v136
	v_lshlrev_b32_e32 v216, 16, v137
	v_and_b32_e32 v217, 0xffff0000, v137
	v_pk_mul_f32 v[210:211], v[250:251], v[210:211] op_sel_hi:[0,1]
	v_pk_mul_f32 v[212:213], v[250:251], v[212:213] op_sel_hi:[0,1]
	v_pk_mul_f32 v[214:215], v[250:251], v[214:215] op_sel_hi:[0,1]
	v_pk_mul_f32 v[216:217], v[250:251], v[216:217] op_sel_hi:[0,1]
	v_pk_mul_f32 v[210:211], v[54:55], v[210:211]
	v_pk_mul_f32 v[212:213], v[56:57], v[212:213]
	v_pk_mul_f32 v[214:215], v[50:51], v[214:215]
	v_pk_mul_f32 v[216:217], v[52:53], v[216:217]
	v_lshlrev_b32_e32 v218, 16, v142
	v_and_b32_e32 v219, 0xffff0000, v142
	v_lshlrev_b32_e32 v220, 16, v143
	v_and_b32_e32 v221, 0xffff0000, v143
	v_lshlrev_b32_e32 v198, 16, v144
	v_and_b32_e32 v199, 0xffff0000, v144
	v_lshlrev_b32_e32 v200, 16, v145
	v_and_b32_e32 v201, 0xffff0000, v145
	v_pk_add_f32 v[210:211], v[210:211], v[218:219]
	v_pk_add_f32 v[212:213], v[212:213], v[220:221]
	v_pk_add_f32 v[214:215], v[214:215], v[198:199]
	v_pk_add_f32 v[216:217], v[216:217], v[200:201]
	v_cvt_pk_bf16_f32 v134, v210, v211
	v_cvt_pk_bf16_f32 v135, v212, v213
	v_cvt_pk_bf16_f32 v136, v214, v215
	v_cvt_pk_bf16_f32 v137, v216, v217
	global_store_dwordx4 v203, v[134:137], s[16:17] offset:256
	ds_read_b32 v205, v195 offset:576
	ds_read_b32 v250, v195 offset:4672
	s_waitcnt lgkmcnt(0)
; __device__ __forceinline__ u32x4 pack8(f32x4 a, f32x4 b) { u32x4 w; w.x = cvt_pk_bf16(a[0], a[1]); w.y = cvt_pk_bf16(a[2], a[3]); w.z = cvt_pk_bf16(b[0], b[1]); w.w = cvt_pk_bf16(b[2], b[3]); return w; }
; __device__ __forceinline__ void unpack8(u32x4 w, f32x4& a, f32x4& b) { a = (f32x4){bflo(w.x), bfhi(w.x), bflo(w.y), bfhi(w.y)}; b = (f32x4){bflo(w.z), bfhi(w.z), bflo(w.w), bfhi(w.w)}; }
; __device__ __forceinline__ float sigmoidf_(float x) { return __builtin_amdgcn_rcpf(1.f + __builtin_amdgcn_exp2f(-1.4426950408889634f * x)); }
;     __device__ __forceinline__ void operator()(AccRef acc, const MUnit& u, int wr, int wc, int fr, int fq) const {
;     ...
;             EPI_ROWS_BEGIN
;                 const float r = rsl[row & 255]; const float ts = (n == 2) ? rsl[1024 + (row & 255)] : 1.f;
; #pragma unroll
;                 for (int bj = 0; bj < 2; ++bj) {
;                     const size_t off = (size_t)row * 1024 + col0 + bj * 128;
;                     f32x4 t0, t1; unpack8(tq[ai][m][bj], t0, t1); t0 = t0 * ts; t1 = t1 * ts;
;                     f32x4 g0 = acc[ai][bj][m][0] * r, g1 = acc[ai][bj][m][1] * r;
; #pragma unroll
;                     for (int e = 0; e < 4; ++e) { g0[e] = sigmoidf_(g0[e]) * t0[e]; g1[e] = sigmoidf_(g1[e]) * t1[e]; }
;                     if (n > 0) { f32x4 p0, p1; unpack8(*(const u32x4*)(mb + off), p0, p1); g0 += p0; g1 += p1; }
;                     *(u32x4*)(mb + off) = pack8(g0, g1);
	v_cndmask_b32_e64 v250, 1.0, v250, s[38:39]
	v_mul_f32_e32 v46, v46, v205
	v_mul_f32_e32 v47, v47, v205
	v_mul_f32_e32 v48, v48, v205
	v_mul_f32_e32 v49, v49, v205
	v_mul_f32_e32 v42, v42, v205
	v_mul_f32_e32 v43, v43, v205
	v_mul_f32_e32 v44, v44, v205
	v_mul_f32_e32 v45, v45, v205
	v_mul_f32_e32 v38, v38, v205
	v_mul_f32_e32 v39, v39, v205
	v_mul_f32_e32 v40, v40, v205
	v_mul_f32_e32 v41, v41, v205
	v_mul_f32_e32 v34, v34, v205
	v_mul_f32_e32 v35, v35, v205
	v_mul_f32_e32 v36, v36, v205
	v_mul_f32_e32 v37, v37, v205
	v_mul_f32_e32 v46, 0xbfb8aa3b, v46
	v_mul_f32_e32 v47, 0xbfb8aa3b, v47
	v_mul_f32_e32 v48, 0xbfb8aa3b, v48
	v_mul_f32_e32 v49, 0xbfb8aa3b, v49
	v_mul_f32_e32 v42, 0xbfb8aa3b, v42
	v_mul_f32_e32 v43, 0xbfb8aa3b, v43
	v_mul_f32_e32 v44, 0xbfb8aa3b, v44
	v_mul_f32_e32 v45, 0xbfb8aa3b, v45
	v_mul_f32_e32 v38, 0xbfb8aa3b, v38
	v_mul_f32_e32 v39, 0xbfb8aa3b, v39
	v_mul_f32_e32 v40, 0xbfb8aa3b, v40
	v_mul_f32_e32 v41, 0xbfb8aa3b, v41
	v_mul_f32_e32 v34, 0xbfb8aa3b, v34
	v_mul_f32_e32 v35, 0xbfb8aa3b, v35
	v_mul_f32_e32 v36, 0xbfb8aa3b, v36
	v_mul_f32_e32 v37, 0xbfb8aa3b, v37
	v_exp_f32_e32 v46, v46
	v_exp_f32_e32 v47, v47
	v_exp_f32_e32 v48, v48
	v_exp_f32_e32 v49, v49
	v_exp_f32_e32 v42, v42
	v_exp_f32_e32 v43, v43
	v_exp_f32_e32 v44, v44
	v_exp_f32_e32 v45, v45
	v_exp_f32_e32 v38, v38
	v_exp_f32_e32 v39, v39
	v_exp_f32_e32 v40, v40
	v_exp_f32_e32 v41, v41
	v_exp_f32_e32 v34, v34
	v_exp_f32_e32 v35, v35
	v_exp_f32_e32 v36, v36
	v_exp_f32_e32 v37, v37
	v_add_f32_e32 v46, 1.0, v46
	v_add_f32_e32 v47, 1.0, v47
	v_add_f32_e32 v48, 1.0, v48
	v_add_f32_e32 v49, 1.0, v49
	v_add_f32_e32 v42, 1.0, v42
	v_add_f32_e32 v43, 1.0, v43
	v_add_f32_e32 v44, 1.0, v44
	v_add_f32_e32 v45, 1.0, v45
	v_add_f32_e32 v38, 1.0, v38
	v_add_f32_e32 v39, 1.0, v39
	v_add_f32_e32 v40, 1.0, v40
	v_add_f32_e32 v41, 1.0, v41
	v_add_f32_e32 v34, 1.0, v34
	v_add_f32_e32 v35, 1.0, v35
	v_add_f32_e32 v36, 1.0, v36
	v_add_f32_e32 v37, 1.0, v37
	v_rcp_f32_e32 v46, v46
	v_rcp_f32_e32 v47, v47
	v_rcp_f32_e32 v48, v48
	v_rcp_f32_e32 v49, v49
	v_rcp_f32_e32 v42, v42
	v_rcp_f32_e32 v43, v43
	v_rcp_f32_e32 v44, v44
	v_rcp_f32_e32 v45, v45
	v_rcp_f32_e32 v38, v38
	v_rcp_f32_e32 v39, v39
	v_rcp_f32_e32 v40, v40
	v_rcp_f32_e32 v41, v41
	v_rcp_f32_e32 v34, v34
	v_rcp_f32_e32 v35, v35
	v_rcp_f32_e32 v36, v36
	v_rcp_f32_e32 v37, v37
	s_waitcnt vmcnt(14)
	v_add_u32_e32 v203, 0x48000, v194
	v_lshlrev_b32_e32 v210, 16, v146
	v_and_b32_e32 v211, 0xffff0000, v146
	v_lshlrev_b32_e32 v212, 16, v147
	v_and_b32_e32 v213, 0xffff0000, v147
	v_lshlrev_b32_e32 v214, 16, v148
	v_and_b32_e32 v215, 0xffff0000, v148
	v_lshlrev_b32_e32 v216, 16, v149
	v_and_b32_e32 v217, 0xffff0000, v149
	v_pk_mul_f32 v[210:211], v[250:251], v[210:211] op_sel_hi:[0,1]
	v_pk_mul_f32 v[212:213], v[250:251], v[212:213] op_sel_hi:[0,1]
	v_pk_mul_f32 v[214:215], v[250:251], v[214:215] op_sel_hi:[0,1]
	v_pk_mul_f32 v[216:217], v[250:251], v[216:217] op_sel_hi:[0,1]
	v_pk_mul_f32 v[210:211], v[46:47], v[210:211]
	v_pk_mul_f32 v[212:213], v[48:49], v[212:213]
	v_pk_mul_f32 v[214:215], v[42:43], v[214:215]
	v_pk_mul_f32 v[216:217], v[44:45], v[216:217]
	v_lshlrev_b32_e32 v218, 16, v154
	v_and_b32_e32 v219, 0xffff0000, v154
	v_lshlrev_b32_e32 v220, 16, v155
	v_and_b32_e32 v221, 0xffff0000, v155
	v_lshlrev_b32_e32 v198, 16, v156
	v_and_b32_e32 v199, 0xffff0000, v156
	v_lshlrev_b32_e32 v200, 16, v157
	v_and_b32_e32 v201, 0xffff0000, v157
	v_pk_add_f32 v[210:211], v[210:211], v[218:219]
	v_pk_add_f32 v[212:213], v[212:213], v[220:221]
	v_pk_add_f32 v[214:215], v[214:215], v[198:199]
	v_pk_add_f32 v[216:217], v[216:217], v[200:201]
	v_cvt_pk_bf16_f32 v146, v210, v211
	v_cvt_pk_bf16_f32 v147, v212, v213
	v_cvt_pk_bf16_f32 v148, v214, v215
	v_cvt_pk_bf16_f32 v149, v216, v217
	global_store_dwordx4 v203, v[146:149], s[16:17]
	v_lshlrev_b32_e32 v210, 16, v150
	v_and_b32_e32 v211, 0xffff0000, v150
	v_lshlrev_b32_e32 v212, 16, v151
	v_and_b32_e32 v213, 0xffff0000, v151
	v_lshlrev_b32_e32 v214, 16, v152
	v_and_b32_e32 v215, 0xffff0000, v152
	v_lshlrev_b32_e32 v216, 16, v153
	v_and_b32_e32 v217, 0xffff0000, v153
	v_pk_mul_f32 v[210:211], v[250:251], v[210:211] op_sel_hi:[0,1]
	v_pk_mul_f32 v[212:213], v[250:251], v[212:213] op_sel_hi:[0,1]
	v_pk_mul_f32 v[214:215], v[250:251], v[214:215] op_sel_hi:[0,1]
	v_pk_mul_f32 v[216:217], v[250:251], v[216:217] op_sel_hi:[0,1]
	v_pk_mul_f32 v[210:211], v[38:39], v[210:211]
	v_pk_mul_f32 v[212:213], v[40:41], v[212:213]
	v_pk_mul_f32 v[214:215], v[34:35], v[214:215]
	v_pk_mul_f32 v[216:217], v[36:37], v[216:217]
	v_lshlrev_b32_e32 v218, 16, v158
	v_and_b32_e32 v219, 0xffff0000, v158
	v_lshlrev_b32_e32 v220, 16, v159
	v_and_b32_e32 v221, 0xffff0000, v159
	v_lshlrev_b32_e32 v198, 16, v160
	v_and_b32_e32 v199, 0xffff0000, v160
	v_lshlrev_b32_e32 v200, 16, v161
	v_and_b32_e32 v201, 0xffff0000, v161
	v_pk_add_f32 v[210:211], v[210:211], v[218:219]
	v_pk_add_f32 v[212:213], v[212:213], v[220:221]
	v_pk_add_f32 v[214:215], v[214:215], v[198:199]
	v_pk_add_f32 v[216:217], v[216:217], v[200:201]
	v_cvt_pk_bf16_f32 v150, v210, v211
	v_cvt_pk_bf16_f32 v151, v212, v213
	v_cvt_pk_bf16_f32 v152, v214, v215
	v_cvt_pk_bf16_f32 v153, v216, v217
	global_store_dwordx4 v203, v[150:153], s[16:17] offset:256
	ds_read_b32 v205, v195 offset:640
	ds_read_b32 v250, v195 offset:4736
	s_waitcnt lgkmcnt(0)
; __device__ __forceinline__ u32x4 pack8(f32x4 a, f32x4 b) { u32x4 w; w.x = cvt_pk_bf16(a[0], a[1]); w.y = cvt_pk_bf16(a[2], a[3]); w.z = cvt_pk_bf16(b[0], b[1]); w.w = cvt_pk_bf16(b[2], b[3]); return w; }
; __device__ __forceinline__ void unpack8(u32x4 w, f32x4& a, f32x4& b) { a = (f32x4){bflo(w.x), bfhi(w.x), bflo(w.y), bfhi(w.y)}; b = (f32x4){bflo(w.z), bfhi(w.z), bflo(w.w), bfhi(w.w)}; }
; __device__ __forceinline__ float sigmoidf_(float x) { return __builtin_amdgcn_rcpf(1.f + __builtin_amdgcn_exp2f(-1.4426950408889634f * x)); }
;     __device__ __forceinline__ void operator()(AccRef acc, const MUnit& u, int wr, int wc, int fr, int fq) const {
;     ...
;             EPI_ROWS_BEGIN
;                 const float r = rsl[row & 255]; const float ts = (n == 2) ? rsl[1024 + (row & 255)] : 1.f;
; #pragma unroll
;                 for (int bj = 0; bj < 2; ++bj) {
;                     const size_t off = (size_t)row * 1024 + col0 + bj * 128;
;                     f32x4 t0, t1; unpack8(tq[ai][m][bj], t0, t1); t0 = t0 * ts; t1 = t1 * ts;
;                     f32x4 g0 = acc[ai][bj][m][0] * r, g1 = acc[ai][bj][m][1] * r;
; #pragma unroll
;                     for (int e = 0; e < 4; ++e) { g0[e] = sigmoidf_(g0[e]) * t0[e]; g1[e] = sigmoidf_(g1[e]) * t1[e]; }
;                     if (n > 0) { f32x4 p0, p1; unpack8(*(const u32x4*)(mb + off), p0, p1); g0 += p0; g1 += p1; }
;                     *(u32x4*)(mb + off) = pack8(g0, g1);
	v_cndmask_b32_e64 v250, 1.0, v250, s[38:39]
	v_mul_f32_e32 v30, v30, v205
	v_mul_f32_e32 v31, v31, v205
	v_mul_f32_e32 v32, v32, v205
	v_mul_f32_e32 v33, v33, v205
	v_mul_f32_e32 v26, v26, v205
	v_mul_f32_e32 v27, v27, v205
	v_mul_f32_e32 v28, v28, v205
	v_mul_f32_e32 v29, v29, v205
	v_mul_f32_e32 v22, v22, v205
	v_mul_f32_e32 v23, v23, v205
	v_mul_f32_e32 v24, v24, v205
	v_mul_f32_e32 v25, v25, v205
	v_mul_f32_e32 v18, v18, v205
	v_mul_f32_e32 v19, v19, v205
	v_mul_f32_e32 v20, v20, v205
	v_mul_f32_e32 v21, v21, v205
	v_mul_f32_e32 v30, 0xbfb8aa3b, v30
	v_mul_f32_e32 v31, 0xbfb8aa3b, v31
	v_mul_f32_e32 v32, 0xbfb8aa3b, v32
	v_mul_f32_e32 v33, 0xbfb8aa3b, v33
	v_mul_f32_e32 v26, 0xbfb8aa3b, v26
	v_mul_f32_e32 v27, 0xbfb8aa3b, v27
	v_mul_f32_e32 v28, 0xbfb8aa3b, v28
	v_mul_f32_e32 v29, 0xbfb8aa3b, v29
	v_mul_f32_e32 v22, 0xbfb8aa3b, v22
	v_mul_f32_e32 v23, 0xbfb8aa3b, v23
	v_mul_f32_e32 v24, 0xbfb8aa3b, v24
	v_mul_f32_e32 v25, 0xbfb8aa3b, v25
	v_mul_f32_e32 v18, 0xbfb8aa3b, v18
	v_mul_f32_e32 v19, 0xbfb8aa3b, v19
	v_mul_f32_e32 v20, 0xbfb8aa3b, v20
	v_mul_f32_e32 v21, 0xbfb8aa3b, v21
	v_exp_f32_e32 v30, v30
	v_exp_f32_e32 v31, v31
	v_exp_f32_e32 v32, v32
	v_exp_f32_e32 v33, v33
	v_exp_f32_e32 v26, v26
	v_exp_f32_e32 v27, v27
	v_exp_f32_e32 v28, v28
	v_exp_f32_e32 v29, v29
	v_exp_f32_e32 v22, v22
	v_exp_f32_e32 v23, v23
	v_exp_f32_e32 v24, v24
	v_exp_f32_e32 v25, v25
	v_exp_f32_e32 v18, v18
	v_exp_f32_e32 v19, v19
	v_exp_f32_e32 v20, v20
	v_exp_f32_e32 v21, v21
	v_add_f32_e32 v30, 1.0, v30
	v_add_f32_e32 v31, 1.0, v31
	v_add_f32_e32 v32, 1.0, v32
	v_add_f32_e32 v33, 1.0, v33
	v_add_f32_e32 v26, 1.0, v26
	v_add_f32_e32 v27, 1.0, v27
	v_add_f32_e32 v28, 1.0, v28
	v_add_f32_e32 v29, 1.0, v29
	v_add_f32_e32 v22, 1.0, v22
	v_add_f32_e32 v23, 1.0, v23
	v_add_f32_e32 v24, 1.0, v24
	v_add_f32_e32 v25, 1.0, v25
	v_add_f32_e32 v18, 1.0, v18
	v_add_f32_e32 v19, 1.0, v19
	v_add_f32_e32 v20, 1.0, v20
	v_add_f32_e32 v21, 1.0, v21
	v_rcp_f32_e32 v30, v30
	v_rcp_f32_e32 v31, v31
	v_rcp_f32_e32 v32, v32
	v_rcp_f32_e32 v33, v33
	v_rcp_f32_e32 v26, v26
	v_rcp_f32_e32 v27, v27
	v_rcp_f32_e32 v28, v28
	v_rcp_f32_e32 v29, v29
	v_rcp_f32_e32 v22, v22
	v_rcp_f32_e32 v23, v23
	v_rcp_f32_e32 v24, v24
	v_rcp_f32_e32 v25, v25
	v_rcp_f32_e32 v18, v18
	v_rcp_f32_e32 v19, v19
	v_rcp_f32_e32 v20, v20
	v_rcp_f32_e32 v21, v21
	s_waitcnt vmcnt(10)
	v_add_u32_e32 v203, 0x50000, v194
	v_lshlrev_b32_e32 v210, 16, v162
	v_and_b32_e32 v211, 0xffff0000, v162
	v_lshlrev_b32_e32 v212, 16, v163
	v_and_b32_e32 v213, 0xffff0000, v163
	v_lshlrev_b32_e32 v214, 16, v164
	v_and_b32_e32 v215, 0xffff0000, v164
	v_lshlrev_b32_e32 v216, 16, v165
	v_and_b32_e32 v217, 0xffff0000, v165
	v_pk_mul_f32 v[210:211], v[250:251], v[210:211] op_sel_hi:[0,1]
	v_pk_mul_f32 v[212:213], v[250:251], v[212:213] op_sel_hi:[0,1]
	v_pk_mul_f32 v[214:215], v[250:251], v[214:215] op_sel_hi:[0,1]
	v_pk_mul_f32 v[216:217], v[250:251], v[216:217] op_sel_hi:[0,1]
	v_pk_mul_f32 v[210:211], v[30:31], v[210:211]
	v_pk_mul_f32 v[212:213], v[32:33], v[212:213]
	v_pk_mul_f32 v[214:215], v[26:27], v[214:215]
	v_pk_mul_f32 v[216:217], v[28:29], v[216:217]
	v_lshlrev_b32_e32 v218, 16, v170
	v_and_b32_e32 v219, 0xffff0000, v170
	v_lshlrev_b32_e32 v220, 16, v171
	v_and_b32_e32 v221, 0xffff0000, v171
	v_lshlrev_b32_e32 v198, 16, v172
	v_and_b32_e32 v199, 0xffff0000, v172
	v_lshlrev_b32_e32 v200, 16, v173
	v_and_b32_e32 v201, 0xffff0000, v173
	v_pk_add_f32 v[210:211], v[210:211], v[218:219]
	v_pk_add_f32 v[212:213], v[212:213], v[220:221]
	v_pk_add_f32 v[214:215], v[214:215], v[198:199]
	v_pk_add_f32 v[216:217], v[216:217], v[200:201]
	v_cvt_pk_bf16_f32 v162, v210, v211
	v_cvt_pk_bf16_f32 v163, v212, v213
	v_cvt_pk_bf16_f32 v164, v214, v215
	v_cvt_pk_bf16_f32 v165, v216, v217
	global_store_dwordx4 v203, v[162:165], s[16:17]
	v_lshlrev_b32_e32 v210, 16, v166
	v_and_b32_e32 v211, 0xffff0000, v166
	v_lshlrev_b32_e32 v212, 16, v167
	v_and_b32_e32 v213, 0xffff0000, v167
	v_lshlrev_b32_e32 v214, 16, v168
	v_and_b32_e32 v215, 0xffff0000, v168
	v_lshlrev_b32_e32 v216, 16, v169
	v_and_b32_e32 v217, 0xffff0000, v169
	v_pk_mul_f32 v[210:211], v[250:251], v[210:211] op_sel_hi:[0,1]
	v_pk_mul_f32 v[212:213], v[250:251], v[212:213] op_sel_hi:[0,1]
	v_pk_mul_f32 v[214:215], v[250:251], v[214:215] op_sel_hi:[0,1]
	v_pk_mul_f32 v[216:217], v[250:251], v[216:217] op_sel_hi:[0,1]
	v_pk_mul_f32 v[210:211], v[22:23], v[210:211]
	v_pk_mul_f32 v[212:213], v[24:25], v[212:213]
	v_pk_mul_f32 v[214:215], v[18:19], v[214:215]
	v_pk_mul_f32 v[216:217], v[20:21], v[216:217]
	v_lshlrev_b32_e32 v218, 16, v174
	v_and_b32_e32 v219, 0xffff0000, v174
	v_lshlrev_b32_e32 v220, 16, v175
	v_and_b32_e32 v221, 0xffff0000, v175
	v_lshlrev_b32_e32 v198, 16, v176
	v_and_b32_e32 v199, 0xffff0000, v176
	v_lshlrev_b32_e32 v200, 16, v177
	v_and_b32_e32 v201, 0xffff0000, v177
	v_pk_add_f32 v[210:211], v[210:211], v[218:219]
	v_pk_add_f32 v[212:213], v[212:213], v[220:221]
	v_pk_add_f32 v[214:215], v[214:215], v[198:199]
	v_pk_add_f32 v[216:217], v[216:217], v[200:201]
	v_cvt_pk_bf16_f32 v166, v210, v211
	v_cvt_pk_bf16_f32 v167, v212, v213
	v_cvt_pk_bf16_f32 v168, v214, v215
	v_cvt_pk_bf16_f32 v169, v216, v217
	global_store_dwordx4 v203, v[166:169], s[16:17] offset:256
	ds_read_b32 v205, v195 offset:704
	ds_read_b32 v250, v195 offset:4800
	s_waitcnt lgkmcnt(0)
; __device__ __forceinline__ u32x4 pack8(f32x4 a, f32x4 b) { u32x4 w; w.x = cvt_pk_bf16(a[0], a[1]); w.y = cvt_pk_bf16(a[2], a[3]); w.z = cvt_pk_bf16(b[0], b[1]); w.w = cvt_pk_bf16(b[2], b[3]); return w; }
; __device__ __forceinline__ void unpack8(u32x4 w, f32x4& a, f32x4& b) { a = (f32x4){bflo(w.x), bfhi(w.x), bflo(w.y), bfhi(w.y)}; b = (f32x4){bflo(w.z), bfhi(w.z), bflo(w.w), bfhi(w.w)}; }
; __device__ __forceinline__ float sigmoidf_(float x) { return __builtin_amdgcn_rcpf(1.f + __builtin_amdgcn_exp2f(-1.4426950408889634f * x)); }
;     __device__ __forceinline__ void operator()(AccRef acc, const MUnit& u, int wr, int wc, int fr, int fq) const {
;     ...
;             EPI_ROWS_BEGIN
;                 const float r = rsl[row & 255]; const float ts = (n == 2) ? rsl[1024 + (row & 255)] : 1.f;
; #pragma unroll
;                 for (int bj = 0; bj < 2; ++bj) {
;                     const size_t off = (size_t)row * 1024 + col0 + bj * 128;
;                     f32x4 t0, t1; unpack8(tq[ai][m][bj], t0, t1); t0 = t0 * ts; t1 = t1 * ts;
;                     f32x4 g0 = acc[ai][bj][m][0] * r, g1 = acc[ai][bj][m][1] * r;
; #pragma unroll
;                     for (int e = 0; e < 4; ++e) { g0[e] = sigmoidf_(g0[e]) * t0[e]; g1[e] = sigmoidf_(g1[e]) * t1[e]; }
;                     if (n > 0) { f32x4 p0, p1; unpack8(*(const u32x4*)(mb + off), p0, p1); g0 += p0; g1 += p1; }
;                     *(u32x4*)(mb + off) = pack8(g0, g1);
	v_cndmask_b32_e64 v250, 1.0, v250, s[38:39]
	v_mul_f32_e32 v14, v14, v205
	v_mul_f32_e32 v15, v15, v205
	v_mul_f32_e32 v16, v16, v205
	v_mul_f32_e32 v17, v17, v205
	v_mul_f32_e32 v10, v10, v205
	v_mul_f32_e32 v11, v11, v205
	v_mul_f32_e32 v12, v12, v205
	v_mul_f32_e32 v13, v13, v205
	v_mul_f32_e32 v6, v6, v205
	v_mul_f32_e32 v7, v7, v205
	v_mul_f32_e32 v8, v8, v205
	v_mul_f32_e32 v9, v9, v205
	v_mul_f32_e32 v2, v2, v205
	v_mul_f32_e32 v3, v3, v205
	v_mul_f32_e32 v4, v4, v205
	v_mul_f32_e32 v5, v5, v205
	v_mul_f32_e32 v14, 0xbfb8aa3b, v14
	v_mul_f32_e32 v15, 0xbfb8aa3b, v15
	v_mul_f32_e32 v16, 0xbfb8aa3b, v16
	v_mul_f32_e32 v17, 0xbfb8aa3b, v17
	v_mul_f32_e32 v10, 0xbfb8aa3b, v10
	v_mul_f32_e32 v11, 0xbfb8aa3b, v11
	v_mul_f32_e32 v12, 0xbfb8aa3b, v12
	v_mul_f32_e32 v13, 0xbfb8aa3b, v13
	v_mul_f32_e32 v6, 0xbfb8aa3b, v6
	v_mul_f32_e32 v7, 0xbfb8aa3b, v7
	v_mul_f32_e32 v8, 0xbfb8aa3b, v8
	v_mul_f32_e32 v9, 0xbfb8aa3b, v9
	v_mul_f32_e32 v2, 0xbfb8aa3b, v2
	v_mul_f32_e32 v3, 0xbfb8aa3b, v3
	v_mul_f32_e32 v4, 0xbfb8aa3b, v4
	v_mul_f32_e32 v5, 0xbfb8aa3b, v5
	v_exp_f32_e32 v14, v14
	v_exp_f32_e32 v15, v15
	v_exp_f32_e32 v16, v16
	v_exp_f32_e32 v17, v17
	v_exp_f32_e32 v10, v10
	v_exp_f32_e32 v11, v11
	v_exp_f32_e32 v12, v12
	v_exp_f32_e32 v13, v13
	v_exp_f32_e32 v6, v6
	v_exp_f32_e32 v7, v7
	v_exp_f32_e32 v8, v8
	v_exp_f32_e32 v9, v9
	v_exp_f32_e32 v2, v2
	v_exp_f32_e32 v3, v3
	v_exp_f32_e32 v4, v4
	v_exp_f32_e32 v5, v5
	v_add_f32_e32 v14, 1.0, v14
	v_add_f32_e32 v15, 1.0, v15
	v_add_f32_e32 v16, 1.0, v16
	v_add_f32_e32 v17, 1.0, v17
	v_add_f32_e32 v10, 1.0, v10
	v_add_f32_e32 v11, 1.0, v11
	v_add_f32_e32 v12, 1.0, v12
	v_add_f32_e32 v13, 1.0, v13
	v_add_f32_e32 v6, 1.0, v6
	v_add_f32_e32 v7, 1.0, v7
	v_add_f32_e32 v8, 1.0, v8
	v_add_f32_e32 v9, 1.0, v9
	v_add_f32_e32 v2, 1.0, v2
	v_add_f32_e32 v3, 1.0, v3
	v_add_f32_e32 v4, 1.0, v4
	v_add_f32_e32 v5, 1.0, v5
	v_rcp_f32_e32 v14, v14
	v_rcp_f32_e32 v15, v15
	v_rcp_f32_e32 v16, v16
	v_rcp_f32_e32 v17, v17
	v_rcp_f32_e32 v10, v10
	v_rcp_f32_e32 v11, v11
	v_rcp_f32_e32 v12, v12
	v_rcp_f32_e32 v13, v13
	v_rcp_f32_e32 v6, v6
	v_rcp_f32_e32 v7, v7
	v_rcp_f32_e32 v8, v8
	v_rcp_f32_e32 v9, v9
	v_rcp_f32_e32 v2, v2
	v_rcp_f32_e32 v3, v3
	v_rcp_f32_e32 v4, v4
	v_rcp_f32_e32 v5, v5
	s_waitcnt vmcnt(6)
	v_add_u32_e32 v203, 0x58000, v194
	v_lshlrev_b32_e32 v210, 16, v178
	v_and_b32_e32 v211, 0xffff0000, v178
	v_lshlrev_b32_e32 v212, 16, v179
	v_and_b32_e32 v213, 0xffff0000, v179
	v_lshlrev_b32_e32 v214, 16, v180
	v_and_b32_e32 v215, 0xffff0000, v180
	v_lshlrev_b32_e32 v216, 16, v181
	v_and_b32_e32 v217, 0xffff0000, v181
	v_pk_mul_f32 v[210:211], v[250:251], v[210:211] op_sel_hi:[0,1]
	v_pk_mul_f32 v[212:213], v[250:251], v[212:213] op_sel_hi:[0,1]
	v_pk_mul_f32 v[214:215], v[250:251], v[214:215] op_sel_hi:[0,1]
	v_pk_mul_f32 v[216:217], v[250:251], v[216:217] op_sel_hi:[0,1]
	v_pk_mul_f32 v[210:211], v[14:15], v[210:211]
	v_pk_mul_f32 v[212:213], v[16:17], v[212:213]
	v_pk_mul_f32 v[214:215], v[10:11], v[214:215]
	v_pk_mul_f32 v[216:217], v[12:13], v[216:217]
	v_lshlrev_b32_e32 v218, 16, v186
	v_and_b32_e32 v219, 0xffff0000, v186
	v_lshlrev_b32_e32 v220, 16, v187
	v_and_b32_e32 v221, 0xffff0000, v187
	v_lshlrev_b32_e32 v198, 16, v188
	v_and_b32_e32 v199, 0xffff0000, v188
	v_lshlrev_b32_e32 v200, 16, v189
	v_and_b32_e32 v201, 0xffff0000, v189
	v_pk_add_f32 v[210:211], v[210:211], v[218:219]
	v_pk_add_f32 v[212:213], v[212:213], v[220:221]
	v_pk_add_f32 v[214:215], v[214:215], v[198:199]
	v_pk_add_f32 v[216:217], v[216:217], v[200:201]
	v_cvt_pk_bf16_f32 v178, v210, v211
	v_cvt_pk_bf16_f32 v179, v212, v213
	v_cvt_pk_bf16_f32 v180, v214, v215
	v_cvt_pk_bf16_f32 v181, v216, v217
	global_store_dwordx4 v203, v[178:181], s[16:17]
	v_lshlrev_b32_e32 v210, 16, v182
	v_and_b32_e32 v211, 0xffff0000, v182
	v_lshlrev_b32_e32 v212, 16, v183
	v_and_b32_e32 v213, 0xffff0000, v183
	v_lshlrev_b32_e32 v214, 16, v184
	v_and_b32_e32 v215, 0xffff0000, v184
	v_lshlrev_b32_e32 v216, 16, v185
	v_and_b32_e32 v217, 0xffff0000, v185
	v_pk_mul_f32 v[210:211], v[250:251], v[210:211] op_sel_hi:[0,1]
	v_pk_mul_f32 v[212:213], v[250:251], v[212:213] op_sel_hi:[0,1]
	v_pk_mul_f32 v[214:215], v[250:251], v[214:215] op_sel_hi:[0,1]
	v_pk_mul_f32 v[216:217], v[250:251], v[216:217] op_sel_hi:[0,1]
	v_pk_mul_f32 v[210:211], v[6:7], v[210:211]
	v_pk_mul_f32 v[212:213], v[8:9], v[212:213]
	v_pk_mul_f32 v[214:215], v[2:3], v[214:215]
	v_pk_mul_f32 v[216:217], v[4:5], v[216:217]
	v_lshlrev_b32_e32 v218, 16, v190
	v_and_b32_e32 v219, 0xffff0000, v190
	v_lshlrev_b32_e32 v220, 16, v191
	v_and_b32_e32 v221, 0xffff0000, v191
	v_lshlrev_b32_e32 v198, 16, v192
	v_and_b32_e32 v199, 0xffff0000, v192
	v_lshlrev_b32_e32 v200, 16, v193
	v_and_b32_e32 v201, 0xffff0000, v193
	v_pk_add_f32 v[210:211], v[210:211], v[218:219]
	v_pk_add_f32 v[212:213], v[212:213], v[220:221]
	v_pk_add_f32 v[214:215], v[214:215], v[198:199]
	v_pk_add_f32 v[216:217], v[216:217], v[200:201]
	v_cvt_pk_bf16_f32 v182, v210, v211
	v_cvt_pk_bf16_f32 v183, v212, v213
	v_cvt_pk_bf16_f32 v184, v214, v215
	v_cvt_pk_bf16_f32 v185, v216, v217
	global_store_dwordx4 v203, v[182:185], s[16:17] offset:256
	s_branch .LBB0_1385
